# attention fast loop: K/V tiles staged HBM->LDS by LDS-DMA (4 K + 4 V buffers, scalar bases) instead of register staging + ds_write
# speedup vs baseline: 1.0582x; 1.0239x over previous
; #define LAS __attribute__((address_space(3)))
; __device__ __forceinline__ unsigned xb_add(unsigned* p, unsigned v) { return __hip_atomic_fetch_add(p, v, __ATOMIC_RELAXED, __HIP_MEMORY_SCOPE_AGENT); }
; __device__ __forceinline__ unsigned xb_xcc_id() { return (unsigned)__builtin_amdgcn_s_getreg((3 << 11) | 20) & 0xFu; }
; __device__ __forceinline__ XcdBarrier xcd_barrier_post(unsigned* bar, volatile LAS unsigned* st) {
;     XcdBarrier b; b.bar = bar; b.x = xb_xcc_id(); b.st = st;
;     if (threadIdx.x == 0) st[2] = xb_add(&bar[XB_XCNT(b.x)], 1u) + 1u;
;     return b;
; __global__ void __launch_bounds__(512, 2) fwd_kernel(Args a) {
;     extern __shared__ __attribute__((aligned(16))) unsigned char lds_raw[];
;     LAS unsigned char* lds = (LAS unsigned char*)lds_raw;
;     const int wid = __builtin_amdgcn_readfirstlane(threadIdx.x >> 6);
;     const int G = gridDim.x, bx0 = blockIdx.x;
;     int bx = bx0;
;     unsigned char* ws = a.ws;
;     bf16_t* P = (bf16_t*)(ws + WS_P); bf16_t* XB = (bf16_t*)(ws + WS_XB);
;     float* SS = (float*)(ws + WS_SS); float* SSV = (float*)(ws + WS_SSV);
;     const float* rope = (const float*)(ws + WS_ROPE);
;     if (threadIdx.x < 4) ((LAS unsigned*)(lds + BARW_OFF))[threadIdx.x] = 0u;
;     __syncthreads();
;     XcdBarrier xbar = xcd_barrier_post((unsigned*)(ws + WS_BAR), (volatile LAS unsigned*)(lds + BARW_OFF));
_Z10fwd_kernel4Args:
	s_load_dwordx2 s[90:91], s[0:1], 0x80
	s_mov_b32 s101, 0
	s_mov_b32 s100, 0
	s_add_u32 s4, s0, 0x90
	s_addc_u32 s5, s1, 0
	v_and_b32_e32 v199, 0x3ff, v0
	v_writelane_b32 v253, s4, 0
	v_readfirstlane_b32 s16, v199
	v_cmp_gt_u32_e32 vcc, 4, v199
	v_writelane_b32 v253, s5, 1
	s_and_saveexec_b64 s[4:5], vcc
	v_lshl_add_u32 v1, v199, 2, 0
	v_add_u32_e32 v1, 0x27000, v1
	v_mov_b32_e32 v2, 0
	ds_write_b32 v1, v2
	s_or_b64 exec, exec, s[4:5]
	s_load_dwordx2 s[4:5], s[0:1], 0x88
	s_load_dword s3, s[0:1], 0x90
	s_waitcnt lgkmcnt(0)
	s_barrier
	v_writelane_b32 v253, s4, 2
	s_getreg_b32 s6, hwreg(HW_REG_XCC_ID, 0, 4)
	v_cmp_eq_u32_e64 s[8:9], 0, v199
	v_writelane_b32 v253, s5, 3
	s_add_u32 s4, s90, 0x1dc2000
	s_addc_u32 s5, s91, 0
	s_and_b32 s13, s6, 15
	s_mov_b64 s[6:7], exec
	v_writelane_b32 v253, s8, 4
	s_nop 1
	v_writelane_b32 v253, s9, 5
	s_and_b64 s[8:9], s[6:7], s[8:9]
	s_mov_b64 exec, s[8:9]
	s_cbranch_execz .LBB0_6
	s_mov_b64 s[10:11], exec
	v_mbcnt_lo_u32_b32 v1, s10, 0
	v_mbcnt_hi_u32_b32 v1, s11, v1
	v_cmp_eq_u32_e32 vcc, 0, v1
	s_and_saveexec_b64 s[8:9], vcc
	s_cbranch_execz .LBB0_5
	s_lshl_b32 s12, s13, 8
	s_bcnt1_i32_b64 s10, s[10:11]
	v_mov_b32_e32 v2, s12
	v_mov_b32_e32 v3, s10
	global_atomic_add v2, v2, v3, s[4:5] offset:1024 sc0

; __device__ __forceinline__ void attn_unit(LAS unsigned char* lds, bf16_t* P, const float* qgain, const float* rope, int s, int h, int qb, int lane, int wid, bool dry) {
;     ...
;     const bf16_t* ksrc = P + (rowbase + lane) * EVEN_IN + 1536 + kvh * 64 + wid * 8;
;     const bf16_t* vsrc = P + (rowbase + 16 * (wid & 3) + (lane >> 2)) * EVEN_IN + 1664 + kvh * 64 + (wid >> 2) * 32 + (lane & 3) * 8;
;     const int kdst = wid * 1024 + lane * 16;
;     const int vdst = 16384 + (wid >> 2) * 4096 + (16 * (wid & 3) + (lane >> 2)) * 64 + (lane & 3) * 16;
.Lfa_g0_entry:
	v_lshl_add_u64 v[146:147], v[174:175], 0, s[46:47]
	v_lshl_add_u64 v[148:149], v[172:173], 0, s[46:47]
	s_nop 0
	v_readfirstlane_b32 s84, v146
	v_readfirstlane_b32 s85, v147
	v_readfirstlane_b32 s82, v148
	v_readfirstlane_b32 s83, v149
	s_nop 3
	v_subrev_u32_e32 v174, s84, v146
	v_subrev_u32_e32 v172, s82, v148
	s_add_u32 s84, s84, 0x88d8c00
	s_addc_u32 s85, s85, 0
	s_add_u32 s82, s82, 0x8890d00
	s_addc_u32 s83, s83, 0
	s_nop 4
	s_lshl_b32 s40, s38, 10
	s_lshr_b32 s41, s38, 2
	s_lshl_b32 s41, s41, 12
	s_and_b32 s39, s38, 3
	s_lshl_b32 s39, s39, 10
	s_add_i32 s41, s41, s39
	s_add_i32 s41, s41, 16384
	s_waitcnt vmcnt(0)
	ds_write_b128 v177, v[134:137] offset:49152
	ds_write_b128 v178, v[138:141] offset:24576
	s_mov_b32 s80, 0
.Lfa_g0_loop:
	s_add_i32 m0, s40, 57344
	s_nop 0
	global_load_lds_dwordx4 v174, s[84:85]
	s_add_i32 m0, s41, 16384
	s_nop 0
	global_load_lds_dwordx4 v172, s[82:83]
	s_add_u32 s84, s84, 0x48000
	s_addc_u32 s85, s85, 0
	s_add_u32 s82, s82, 0x48000
	s_addc_u32 s83, s83, 0
	ds_read_b128 v[80:83], v179 offset:8192
	ds_read_b128 v[182:185], v179 offset:8704
	ds_read_b128 v[186:189], v179 offset:10240
	ds_read_b128 v[190:193], v179 offset:10752
	ds_read_b128 v[200:203], v179 offset:12288
	ds_read_b128 v[204:207], v179 offset:12800
	ds_read_b128 v[208:211], v179 offset:14336
	ds_read_b128 v[212:215], v179 offset:14848
	v_exp_f32_e32 v64, v64
	v_exp_f32_e32 v65, v65
	v_exp_f32_e32 v66, v66
	v_exp_f32_e32 v67, v67
	v_exp_f32_e32 v48, v48
	v_exp_f32_e32 v49, v49
	v_exp_f32_e32 v50, v50
	v_exp_f32_e32 v51, v51
	v_add_f32_e32 v84, v50, v66
	v_add_f32_e32 v85, v51, v67
	v_add_f32_e32 v86, v48, v64
	v_add_f32_e32 v87, v49, v65
	v_cvt_pk_bf16_f32 v64, v64, v65
	v_cvt_pk_bf16_f32 v65, v66, v67
	v_cvt_pk_bf16_f32 v48, v48, v49
	v_cvt_pk_bf16_f32 v49, v50, v51
	s_waitcnt lgkmcnt(7)
	v_mfma_f32_32x32x16_bf16 v[96:111], v[80:83], v[118:121], v[32:47]
	v_exp_f32_e32 v50, v68
	v_exp_f32_e32 v51, v69
	v_exp_f32_e32 v68, v70
	v_exp_f32_e32 v69, v71
	v_add_f32_e32 v70, v50, v86
	v_add_f32_e32 v71, v51, v87
	v_add_f32_e32 v181, v68, v84
	v_add_f32_e32 v228, v69, v85
	v_cvt_pk_bf16_f32 v66, v50, v51
	v_cvt_pk_bf16_f32 v67, v68, v69
	s_waitcnt lgkmcnt(6)
	v_mfma_f32_32x32x16_bf16 v[80:95], v[182:185], v[118:121], v[32:47]
	v_exp_f32_e32 v50, v52
	v_exp_f32_e32 v51, v53
	v_exp_f32_e32 v52, v54
	v_exp_f32_e32 v53, v55
	v_add_f32_e32 v54, v50, v70
	v_add_f32_e32 v55, v51, v71
	v_add_f32_e32 v68, v52, v181
	v_add_f32_e32 v69, v53, v228
	v_cvt_pk_bf16_f32 v50, v50, v51
	v_cvt_pk_bf16_f32 v51, v52, v53
	s_waitcnt lgkmcnt(5)
	v_mfma_f32_32x32x16_bf16 v[96:111], v[186:189], v[122:125], v[96:111]
	v_exp_f32_e32 v52, v72
	v_exp_f32_e32 v53, v73
	v_exp_f32_e32 v70, v74
	v_exp_f32_e32 v71, v75
	v_add_f32_e32 v54, v52, v54
	v_add_f32_e32 v55, v53, v55
	v_add_f32_e32 v72, v70, v68
	v_add_f32_e32 v73, v71, v69
	v_cvt_pk_bf16_f32 v68, v52, v53
	v_cvt_pk_bf16_f32 v69, v70, v71
	s_waitcnt lgkmcnt(4)
	v_mfma_f32_32x32x16_bf16 v[80:95], v[190:193], v[122:125], v[80:95]
	v_exp_f32_e32 v52, v56
	v_exp_f32_e32 v53, v57
	v_exp_f32_e32 v57, v58
	v_exp_f32_e32 v58, v59
	v_add_f32_e32 v54, v52, v54
	v_add_f32_e32 v55, v53, v55
	v_add_f32_e32 v59, v57, v72
	v_add_f32_e32 v70, v58, v73
	v_cvt_pk_bf16_f32 v56, v52, v53
	v_cvt_pk_bf16_f32 v57, v57, v58
	s_waitcnt lgkmcnt(3)
	v_mfma_f32_32x32x16_bf16 v[96:111], v[200:203], v[126:129], v[96:111]
	v_exp_f32_e32 v52, v76
	v_exp_f32_e32 v53, v77
	v_exp_f32_e32 v58, v78
	v_exp_f32_e32 v71, v79
	v_add_f32_e32 v54, v52, v54
	v_add_f32_e32 v55, v53, v55
	v_add_f32_e32 v59, v58, v59
	v_add_f32_e32 v72, v71, v70
	v_cvt_pk_bf16_f32 v70, v52, v53
	v_cvt_pk_bf16_f32 v71, v58, v71
	s_waitcnt lgkmcnt(2)
	v_mfma_f32_32x32x16_bf16 v[80:95], v[204:207], v[126:129], v[80:95]
	v_exp_f32_e32 v58, v60
	v_exp_f32_e32 v60, v61
	v_exp_f32_e32 v61, v62
	v_exp_f32_e32 v62, v63
	v_add_f32_e32 v52, v58, v54
	v_add_f32_e32 v53, v60, v55
	v_add_f32_e32 v54, v61, v59
	v_add_f32_e32 v55, v62, v72
	v_cvt_pk_bf16_f32 v58, v58, v60
	v_cvt_pk_bf16_f32 v59, v61, v62
	s_waitcnt lgkmcnt(1)
	v_mfma_f32_32x32x16_bf16 v[96:111], v[208:211], v[130:133], v[96:111]
	ds_read_b64_tr_b16 v[60:61], v180 offset:16384
	ds_read_b64_tr_b16 v[62:63], v180 offset:16896
	ds_read_b64_tr_b16 v[72:73], v180 offset:20480
	ds_read_b64_tr_b16 v[74:75], v180 offset:20992
	s_waitcnt lgkmcnt(4)
	v_mfma_f32_32x32x16_bf16 v[80:95], v[212:215], v[130:133], v[80:95]
	s_waitcnt lgkmcnt(2)
	v_mfma_f32_32x32x16_bf16 v[16:31], v[60:63], v[64:67], v[16:31]
	s_waitcnt lgkmcnt(0)
	v_mfma_f32_32x32x16_bf16 v[0:15], v[72:75], v[64:67], v[0:15]
	ds_read_b64_tr_b16 v[60:61], v180 offset:17408
	ds_read_b64_tr_b16 v[62:63], v180 offset:17920
	ds_read_b64_tr_b16 v[64:65], v180 offset:21504
	ds_read_b64_tr_b16 v[66:67], v180 offset:22016
	s_waitcnt lgkmcnt(2)
	v_mfma_f32_32x32x16_bf16 v[16:31], v[60:63], v[68:71], v[16:31]
	s_waitcnt lgkmcnt(0)
	v_mfma_f32_32x32x16_bf16 v[0:15], v[64:67], v[68:71], v[0:15]
	ds_read_b64_tr_b16 v[60:61], v180 offset:18432
	ds_read_b64_tr_b16 v[62:63], v180 offset:18944
	ds_read_b64_tr_b16 v[64:65], v180 offset:22528
	ds_read_b64_tr_b16 v[66:67], v180 offset:23040
	s_waitcnt lgkmcnt(2)
	v_mfma_f32_32x32x16_bf16 v[16:31], v[60:63], v[48:51], v[16:31]
	s_waitcnt lgkmcnt(0)
	v_mfma_f32_32x32x16_bf16 v[0:15], v[64:67], v[48:51], v[0:15]
	ds_read_b64_tr_b16 v[48:49], v180 offset:19456
	ds_read_b64_tr_b16 v[50:51], v180 offset:19968
	ds_read_b64_tr_b16 v[60:61], v180 offset:23552
	ds_read_b64_tr_b16 v[62:63], v180 offset:24064
	s_waitcnt lgkmcnt(2)
	v_mfma_f32_32x32x16_bf16 v[16:31], v[48:51], v[56:59], v[16:31]
	s_waitcnt lgkmcnt(0)
	v_mfma_f32_32x32x16_bf16 v[0:15], v[60:63], v[56:59], v[0:15]
	v_add_f32_e32 v182, v52, v53
	v_add_f32_e32 v183, v54, v55
	v_add_f32_e32 v182, v182, v183
	v_add_f32_e32 v169, v169, v182
	s_waitcnt vmcnt(2)
	s_waitcnt lgkmcnt(0)
	s_barrier
	s_add_i32 m0, s40, 0
	s_nop 0
	global_load_lds_dwordx4 v174, s[84:85]
	s_add_i32 m0, s41, 24576
	s_nop 0
	global_load_lds_dwordx4 v172, s[82:83]
	s_add_u32 s84, s84, 0x48000
	s_addc_u32 s85, s85, 0
	s_add_u32 s82, s82, 0x48000
	s_addc_u32 s83, s83, 0
	ds_read_b128 v[182:185], v179 offset:49152
	ds_read_b128 v[186:189], v179 offset:49664
	ds_read_b128 v[190:193], v179 offset:51200
	ds_read_b128 v[200:203], v179 offset:51712
	ds_read_b128 v[204:207], v179 offset:53248
	ds_read_b128 v[208:211], v179 offset:53760
	ds_read_b128 v[212:215], v179 offset:55296
	ds_read_b128 v[146:149], v179 offset:55808
	v_exp_f32_e32 v64, v96
	v_exp_f32_e32 v65, v97
	v_exp_f32_e32 v66, v98
	v_exp_f32_e32 v67, v99
	v_cvt_pk_bf16_f32 v96, v64, v65
	v_cvt_pk_bf16_f32 v97, v66, v67
	v_exp_f32_e32 v68, v80
	v_exp_f32_e32 v69, v81
	v_exp_f32_e32 v70, v82
	v_exp_f32_e32 v71, v83
	v_cvt_pk_bf16_f32 v80, v68, v69
	v_cvt_pk_bf16_f32 v81, v70, v71
	v_add_f32_e32 v68, v68, v64
	v_add_f32_e32 v69, v69, v65
	v_add_f32_e32 v82, v70, v66
	v_add_f32_e32 v83, v71, v67
	v_exp_f32_e32 v98, v100
	v_exp_f32_e32 v99, v101
	v_exp_f32_e32 v100, v102
	v_exp_f32_e32 v101, v103
	v_add_f32_e32 v102, v98, v68
	v_add_f32_e32 v103, v99, v69
	s_waitcnt lgkmcnt(7)
	v_mfma_f32_32x32x16_bf16 v[64:79], v[182:185], v[118:121], v[32:47]
	v_add_f32_e32 v82, v100, v82
	v_add_f32_e32 v83, v101, v83
	v_cvt_pk_bf16_f32 v98, v98, v99
	v_cvt_pk_bf16_f32 v99, v100, v101
	s_waitcnt lgkmcnt(6)
	v_mfma_f32_32x32x16_bf16 v[48:63], v[186:189], v[118:121], v[32:47]
	v_exp_f32_e32 v84, v84
	v_exp_f32_e32 v85, v85
	v_exp_f32_e32 v86, v86
	v_exp_f32_e32 v87, v87
	v_add_f32_e32 v100, v84, v102
	v_add_f32_e32 v101, v85, v103
	v_add_f32_e32 v102, v86, v82
	v_add_f32_e32 v103, v87, v83
	v_cvt_pk_bf16_f32 v82, v84, v85
	v_cvt_pk_bf16_f32 v83, v86, v87
	s_waitcnt lgkmcnt(5)
	v_mfma_f32_32x32x16_bf16 v[64:79], v[190:193], v[122:125], v[64:79]
	v_exp_f32_e32 v84, v104
	v_exp_f32_e32 v85, v105
	v_exp_f32_e32 v86, v106
	v_exp_f32_e32 v87, v107
	v_add_f32_e32 v104, v84, v100
	v_add_f32_e32 v105, v85, v101
	v_add_f32_e32 v102, v86, v102
	v_add_f32_e32 v103, v87, v103
	v_cvt_pk_bf16_f32 v100, v84, v85
	v_cvt_pk_bf16_f32 v101, v86, v87
	s_waitcnt lgkmcnt(4)
	v_mfma_f32_32x32x16_bf16 v[48:63], v[200:203], v[122:125], v[48:63]
	v_exp_f32_e32 v84, v88
	v_exp_f32_e32 v85, v89
	v_exp_f32_e32 v86, v90
	v_exp_f32_e32 v87, v91
	v_add_f32_e32 v90, v84, v104
	v_add_f32_e32 v91, v85, v105
	v_add_f32_e32 v102, v86, v102
	v_add_f32_e32 v103, v87, v103
	v_cvt_pk_bf16_f32 v88, v84, v85
	v_cvt_pk_bf16_f32 v89, v86, v87
	s_waitcnt lgkmcnt(3)
	v_mfma_f32_32x32x16_bf16 v[64:79], v[204:207], v[126:129], v[64:79]
	v_exp_f32_e32 v84, v108
	v_exp_f32_e32 v85, v109
	v_exp_f32_e32 v86, v110
	v_exp_f32_e32 v87, v111
	v_add_f32_e32 v90, v84, v90
	v_add_f32_e32 v91, v85, v91
	v_add_f32_e32 v104, v86, v102
	v_add_f32_e32 v105, v87, v103
	v_cvt_pk_bf16_f32 v102, v84, v85
	v_cvt_pk_bf16_f32 v103, v86, v87
	s_waitcnt lgkmcnt(2)
	v_mfma_f32_32x32x16_bf16 v[48:63], v[208:211], v[126:129], v[48:63]
	v_exp_f32_e32 v92, v92
	v_exp_f32_e32 v93, v93
	v_exp_f32_e32 v94, v94
	v_exp_f32_e32 v95, v95
	v_add_f32_e32 v84, v92, v90
	v_add_f32_e32 v85, v93, v91
	v_add_f32_e32 v86, v94, v104
	v_add_f32_e32 v87, v95, v105
	v_cvt_pk_bf16_f32 v90, v92, v93
	v_cvt_pk_bf16_f32 v91, v94, v95
	s_waitcnt lgkmcnt(1)
	v_mfma_f32_32x32x16_bf16 v[64:79], v[212:215], v[130:133], v[64:79]
	ds_read_b64_tr_b16 v[92:93], v180 offset:24576
	ds_read_b64_tr_b16 v[94:95], v180 offset:25088
	ds_read_b64_tr_b16 v[104:105], v180 offset:28672
	ds_read_b64_tr_b16 v[106:107], v180 offset:29184
	s_waitcnt lgkmcnt(4)
	v_mfma_f32_32x32x16_bf16 v[48:63], v[146:149], v[130:133], v[48:63]
	s_waitcnt lgkmcnt(2)
	v_mfma_f32_32x32x16_bf16 v[16:31], v[92:95], v[96:99], v[16:31]
	s_waitcnt lgkmcnt(0)
	v_mfma_f32_32x32x16_bf16 v[0:15], v[104:107], v[96:99], v[0:15]
	ds_read_b64_tr_b16 v[92:93], v180 offset:25600
	ds_read_b64_tr_b16 v[94:95], v180 offset:26112
	ds_read_b64_tr_b16 v[96:97], v180 offset:29696
	ds_read_b64_tr_b16 v[98:99], v180 offset:30208
	s_waitcnt lgkmcnt(2)
	v_mfma_f32_32x32x16_bf16 v[16:31], v[92:95], v[100:103], v[16:31]
	s_waitcnt lgkmcnt(0)
	v_mfma_f32_32x32x16_bf16 v[0:15], v[96:99], v[100:103], v[0:15]
	ds_read_b64_tr_b16 v[92:93], v180 offset:26624
	ds_read_b64_tr_b16 v[94:95], v180 offset:27136
	ds_read_b64_tr_b16 v[96:97], v180 offset:30720
	ds_read_b64_tr_b16 v[98:99], v180 offset:31232
	s_waitcnt lgkmcnt(2)
	v_mfma_f32_32x32x16_bf16 v[16:31], v[92:95], v[80:83], v[16:31]
	s_waitcnt lgkmcnt(0)
	v_mfma_f32_32x32x16_bf16 v[0:15], v[96:99], v[80:83], v[0:15]
	ds_read_b64_tr_b16 v[80:81], v180 offset:27648
	ds_read_b64_tr_b16 v[82:83], v180 offset:28160
	ds_read_b64_tr_b16 v[92:93], v180 offset:31744
	ds_read_b64_tr_b16 v[94:95], v180 offset:32256
	s_waitcnt lgkmcnt(2)
	v_mfma_f32_32x32x16_bf16 v[16:31], v[80:83], v[88:91], v[16:31]
	s_waitcnt lgkmcnt(0)
	v_mfma_f32_32x32x16_bf16 v[0:15], v[92:95], v[88:91], v[0:15]
	v_add_f32_e32 v182, v84, v85
	v_add_f32_e32 v183, v86, v87
	v_add_f32_e32 v182, v182, v183
	v_add_f32_e32 v169, v169, v182
	s_waitcnt vmcnt(2)
	s_waitcnt lgkmcnt(0)
	s_barrier
	s_add_i32 m0, s40, 8192
	s_nop 0
	global_load_lds_dwordx4 v174, s[84:85]
	s_add_i32 m0, s41, 0
	s_nop 0
	global_load_lds_dwordx4 v172, s[82:83]
	s_add_u32 s84, s84, 0x48000
	s_addc_u32 s85, s85, 0
	s_add_u32 s82, s82, 0x48000
	s_addc_u32 s83, s83, 0
	ds_read_b128 v[80:83], v179 offset:57344
	ds_read_b128 v[182:185], v179 offset:57856
	ds_read_b128 v[186:189], v179 offset:59392
	ds_read_b128 v[190:193], v179 offset:59904
	ds_read_b128 v[200:203], v179 offset:61440
	ds_read_b128 v[204:207], v179 offset:61952
	ds_read_b128 v[208:211], v179 offset:63488
	ds_read_b128 v[212:215], v179 offset:64000
	v_exp_f32_e32 v64, v64
	v_exp_f32_e32 v65, v65
	v_exp_f32_e32 v66, v66
	v_exp_f32_e32 v67, v67
	v_exp_f32_e32 v48, v48
	v_exp_f32_e32 v49, v49
	v_exp_f32_e32 v50, v50
	v_exp_f32_e32 v51, v51
	v_add_f32_e32 v84, v50, v66
	v_add_f32_e32 v85, v51, v67
	v_add_f32_e32 v86, v48, v64
	v_add_f32_e32 v87, v49, v65
	v_cvt_pk_bf16_f32 v64, v64, v65
	v_cvt_pk_bf16_f32 v65, v66, v67
	v_cvt_pk_bf16_f32 v48, v48, v49
	v_cvt_pk_bf16_f32 v49, v50, v51
	s_waitcnt lgkmcnt(7)
	v_mfma_f32_32x32x16_bf16 v[96:111], v[80:83], v[118:121], v[32:47]
	v_exp_f32_e32 v50, v68
	v_exp_f32_e32 v51, v69
	v_exp_f32_e32 v68, v70
	v_exp_f32_e32 v69, v71
	v_add_f32_e32 v70, v50, v86
	v_add_f32_e32 v71, v51, v87
	v_add_f32_e32 v181, v68, v84
	v_add_f32_e32 v228, v69, v85
	v_cvt_pk_bf16_f32 v66, v50, v51
	v_cvt_pk_bf16_f32 v67, v68, v69
	s_waitcnt lgkmcnt(6)
	v_mfma_f32_32x32x16_bf16 v[80:95], v[182:185], v[118:121], v[32:47]
	v_exp_f32_e32 v50, v52
	v_exp_f32_e32 v51, v53
	v_exp_f32_e32 v52, v54
	v_exp_f32_e32 v53, v55
	v_add_f32_e32 v54, v50, v70
	v_add_f32_e32 v55, v51, v71
	v_add_f32_e32 v68, v52, v181
	v_add_f32_e32 v69, v53, v228
	v_cvt_pk_bf16_f32 v50, v50, v51
	v_cvt_pk_bf16_f32 v51, v52, v53
	s_waitcnt lgkmcnt(5)
	v_mfma_f32_32x32x16_bf16 v[96:111], v[186:189], v[122:125], v[96:111]
	v_exp_f32_e32 v52, v72
	v_exp_f32_e32 v53, v73
	v_exp_f32_e32 v70, v74
	v_exp_f32_e32 v71, v75
	v_add_f32_e32 v54, v52, v54
	v_add_f32_e32 v55, v53, v55
	v_add_f32_e32 v72, v70, v68
	v_add_f32_e32 v73, v71, v69
	v_cvt_pk_bf16_f32 v68, v52, v53
	v_cvt_pk_bf16_f32 v69, v70, v71
	s_waitcnt lgkmcnt(4)
	v_mfma_f32_32x32x16_bf16 v[80:95], v[190:193], v[122:125], v[80:95]
	v_exp_f32_e32 v52, v56
	v_exp_f32_e32 v53, v57
	v_exp_f32_e32 v57, v58
	v_exp_f32_e32 v58, v59
	v_add_f32_e32 v54, v52, v54
	v_add_f32_e32 v55, v53, v55
	v_add_f32_e32 v59, v57, v72
	v_add_f32_e32 v70, v58, v73
	v_cvt_pk_bf16_f32 v56, v52, v53
	v_cvt_pk_bf16_f32 v57, v57, v58
	s_waitcnt lgkmcnt(3)
	v_mfma_f32_32x32x16_bf16 v[96:111], v[200:203], v[126:129], v[96:111]
	v_exp_f32_e32 v52, v76
	v_exp_f32_e32 v53, v77
	v_exp_f32_e32 v58, v78
	v_exp_f32_e32 v71, v79
	v_add_f32_e32 v54, v52, v54
	v_add_f32_e32 v55, v53, v55
	v_add_f32_e32 v59, v58, v59
	v_add_f32_e32 v72, v71, v70
	v_cvt_pk_bf16_f32 v70, v52, v53
	v_cvt_pk_bf16_f32 v71, v58, v71
	s_waitcnt lgkmcnt(2)
	v_mfma_f32_32x32x16_bf16 v[80:95], v[204:207], v[126:129], v[80:95]
	v_exp_f32_e32 v58, v60
	v_exp_f32_e32 v60, v61
	v_exp_f32_e32 v61, v62
	v_exp_f32_e32 v62, v63
	v_add_f32_e32 v52, v58, v54
	v_add_f32_e32 v53, v60, v55
	v_add_f32_e32 v54, v61, v59
	v_add_f32_e32 v55, v62, v72
	v_cvt_pk_bf16_f32 v58, v58, v60
	v_cvt_pk_bf16_f32 v59, v61, v62
	s_waitcnt lgkmcnt(1)
	v_mfma_f32_32x32x16_bf16 v[96:111], v[208:211], v[130:133], v[96:111]
	ds_read_b64_tr_b16 v[60:61], v180 offset:32768
	ds_read_b64_tr_b16 v[62:63], v180 offset:33280
	ds_read_b64_tr_b16 v[72:73], v180 offset:36864
	ds_read_b64_tr_b16 v[74:75], v180 offset:37376
	s_waitcnt lgkmcnt(4)
	v_mfma_f32_32x32x16_bf16 v[80:95], v[212:215], v[130:133], v[80:95]
	s_waitcnt lgkmcnt(2)
	v_mfma_f32_32x32x16_bf16 v[16:31], v[60:63], v[64:67], v[16:31]
	s_waitcnt lgkmcnt(0)
	v_mfma_f32_32x32x16_bf16 v[0:15], v[72:75], v[64:67], v[0:15]
	ds_read_b64_tr_b16 v[60:61], v180 offset:33792
	ds_read_b64_tr_b16 v[62:63], v180 offset:34304
	ds_read_b64_tr_b16 v[64:65], v180 offset:37888
	ds_read_b64_tr_b16 v[66:67], v180 offset:38400
	s_waitcnt lgkmcnt(2)
	v_mfma_f32_32x32x16_bf16 v[16:31], v[60:63], v[68:71], v[16:31]
	s_waitcnt lgkmcnt(0)
	v_mfma_f32_32x32x16_bf16 v[0:15], v[64:67], v[68:71], v[0:15]
	ds_read_b64_tr_b16 v[60:61], v180 offset:34816
	ds_read_b64_tr_b16 v[62:63], v180 offset:35328
	ds_read_b64_tr_b16 v[64:65], v180 offset:38912
	ds_read_b64_tr_b16 v[66:67], v180 offset:39424
	s_waitcnt lgkmcnt(2)
	v_mfma_f32_32x32x16_bf16 v[16:31], v[60:63], v[48:51], v[16:31]
	s_waitcnt lgkmcnt(0)
	v_mfma_f32_32x32x16_bf16 v[0:15], v[64:67], v[48:51], v[0:15]
	ds_read_b64_tr_b16 v[48:49], v180 offset:35840
	ds_read_b64_tr_b16 v[50:51], v180 offset:36352
	ds_read_b64_tr_b16 v[60:61], v180 offset:39936
	ds_read_b64_tr_b16 v[62:63], v180 offset:40448
	s_waitcnt lgkmcnt(2)
	v_mfma_f32_32x32x16_bf16 v[16:31], v[48:51], v[56:59], v[16:31]
	s_waitcnt lgkmcnt(0)
	v_mfma_f32_32x32x16_bf16 v[0:15], v[60:63], v[56:59], v[0:15]
	v_add_f32_e32 v182, v52, v53
	v_add_f32_e32 v183, v54, v55
	v_add_f32_e32 v182, v182, v183
	v_add_f32_e32 v169, v169, v182
	s_waitcnt vmcnt(2)
	s_waitcnt lgkmcnt(0)
	s_barrier
; __device__ __forceinline__ void attn_unit(LAS unsigned char* lds, bf16_t* P, const float* qgain, const float* rope, int s, int h, int qb, int lane, int wid, bool dry) {
;     ...
;     for (int t = 0; t < NT; t += 2) {
;         ASTEP(t, pA0, pA1, pB0, pB1, krA, vrA, krB, vrB);
;         ASTEP(t + 1, pB0, pB1, pA0, pA1, krB, vrB, krA, vrA);
;     }
	s_add_i32 m0, s40, 49152
	s_nop 0
	global_load_lds_dwordx4 v174, s[84:85]
	s_add_i32 m0, s41, 8192
	s_nop 0
	global_load_lds_dwordx4 v172, s[82:83]
	s_add_u32 s84, s84, 0x48000
	s_addc_u32 s85, s85, 0
	s_add_u32 s82, s82, 0x48000
	s_addc_u32 s83, s83, 0
	ds_read_b128 v[182:185], v179
	ds_read_b128 v[186:189], v179 offset:512
	ds_read_b128 v[190:193], v179 offset:2048
	ds_read_b128 v[200:203], v179 offset:2560
	ds_read_b128 v[204:207], v179 offset:4096
	ds_read_b128 v[208:211], v179 offset:4608
	ds_read_b128 v[212:215], v179 offset:6144
	ds_read_b128 v[146:149], v179 offset:6656
	v_exp_f32_e32 v64, v96
	v_exp_f32_e32 v65, v97
	v_exp_f32_e32 v66, v98
	v_exp_f32_e32 v67, v99
	v_cvt_pk_bf16_f32 v96, v64, v65
	v_cvt_pk_bf16_f32 v97, v66, v67
	v_exp_f32_e32 v68, v80
	v_exp_f32_e32 v69, v81
	v_exp_f32_e32 v70, v82
	v_exp_f32_e32 v71, v83
	v_cvt_pk_bf16_f32 v80, v68, v69
	v_cvt_pk_bf16_f32 v81, v70, v71
	v_add_f32_e32 v68, v68, v64
	v_add_f32_e32 v69, v69, v65
	v_add_f32_e32 v82, v70, v66
	v_add_f32_e32 v83, v71, v67
	v_exp_f32_e32 v98, v100
	v_exp_f32_e32 v99, v101
	v_exp_f32_e32 v100, v102
	v_exp_f32_e32 v101, v103
	v_add_f32_e32 v102, v98, v68
	v_add_f32_e32 v103, v99, v69
	s_waitcnt lgkmcnt(7)
	v_mfma_f32_32x32x16_bf16 v[64:79], v[182:185], v[118:121], v[32:47]
	v_add_f32_e32 v82, v100, v82
	v_add_f32_e32 v83, v101, v83
	v_cvt_pk_bf16_f32 v98, v98, v99
	v_cvt_pk_bf16_f32 v99, v100, v101
	s_waitcnt lgkmcnt(6)
	v_mfma_f32_32x32x16_bf16 v[48:63], v[186:189], v[118:121], v[32:47]
	v_exp_f32_e32 v84, v84
	v_exp_f32_e32 v85, v85
	v_exp_f32_e32 v86, v86
	v_exp_f32_e32 v87, v87
	v_add_f32_e32 v100, v84, v102
	v_add_f32_e32 v101, v85, v103
	v_add_f32_e32 v102, v86, v82
	v_add_f32_e32 v103, v87, v83
	v_cvt_pk_bf16_f32 v82, v84, v85
	v_cvt_pk_bf16_f32 v83, v86, v87
	s_waitcnt lgkmcnt(5)
	v_mfma_f32_32x32x16_bf16 v[64:79], v[190:193], v[122:125], v[64:79]
	v_exp_f32_e32 v84, v104
	v_exp_f32_e32 v85, v105
	v_exp_f32_e32 v86, v106
	v_exp_f32_e32 v87, v107
	v_add_f32_e32 v104, v84, v100
	v_add_f32_e32 v105, v85, v101
	v_add_f32_e32 v102, v86, v102
	v_add_f32_e32 v103, v87, v103
	v_cvt_pk_bf16_f32 v100, v84, v85
	v_cvt_pk_bf16_f32 v101, v86, v87
	s_waitcnt lgkmcnt(4)
	v_mfma_f32_32x32x16_bf16 v[48:63], v[200:203], v[122:125], v[48:63]
	v_exp_f32_e32 v84, v88
	v_exp_f32_e32 v85, v89
	v_exp_f32_e32 v86, v90
	v_exp_f32_e32 v87, v91
	v_add_f32_e32 v90, v84, v104
	v_add_f32_e32 v91, v85, v105
	v_add_f32_e32 v102, v86, v102
	v_add_f32_e32 v103, v87, v103
	v_cvt_pk_bf16_f32 v88, v84, v85
	v_cvt_pk_bf16_f32 v89, v86, v87
	s_waitcnt lgkmcnt(3)
	v_mfma_f32_32x32x16_bf16 v[64:79], v[204:207], v[126:129], v[64:79]
	v_exp_f32_e32 v84, v108
	v_exp_f32_e32 v85, v109
	v_exp_f32_e32 v86, v110
	v_exp_f32_e32 v87, v111
	v_add_f32_e32 v90, v84, v90
	v_add_f32_e32 v91, v85, v91
	v_add_f32_e32 v104, v86, v102
	v_add_f32_e32 v105, v87, v103
	v_cvt_pk_bf16_f32 v102, v84, v85
	v_cvt_pk_bf16_f32 v103, v86, v87
	s_waitcnt lgkmcnt(2)
	v_mfma_f32_32x32x16_bf16 v[48:63], v[208:211], v[126:129], v[48:63]
	v_exp_f32_e32 v92, v92
	v_exp_f32_e32 v93, v93
	v_exp_f32_e32 v94, v94
	v_exp_f32_e32 v95, v95
	v_add_f32_e32 v84, v92, v90
	v_add_f32_e32 v85, v93, v91
	v_add_f32_e32 v86, v94, v104
	v_add_f32_e32 v87, v95, v105
	v_cvt_pk_bf16_f32 v90, v92, v93
	v_cvt_pk_bf16_f32 v91, v94, v95
	s_waitcnt lgkmcnt(1)
	v_mfma_f32_32x32x16_bf16 v[64:79], v[212:215], v[130:133], v[64:79]
	ds_read_b64_tr_b16 v[92:93], v180 offset:40960
	ds_read_b64_tr_b16 v[94:95], v180 offset:41472
	ds_read_b64_tr_b16 v[104:105], v180 offset:45056
	ds_read_b64_tr_b16 v[106:107], v180 offset:45568
	s_waitcnt lgkmcnt(4)
	v_mfma_f32_32x32x16_bf16 v[48:63], v[146:149], v[130:133], v[48:63]
	s_waitcnt lgkmcnt(2)
	v_mfma_f32_32x32x16_bf16 v[16:31], v[92:95], v[96:99], v[16:31]
	s_waitcnt lgkmcnt(0)
	v_mfma_f32_32x32x16_bf16 v[0:15], v[104:107], v[96:99], v[0:15]
	ds_read_b64_tr_b16 v[92:93], v180 offset:41984
	ds_read_b64_tr_b16 v[94:95], v180 offset:42496
	ds_read_b64_tr_b16 v[96:97], v180 offset:46080
	ds_read_b64_tr_b16 v[98:99], v180 offset:46592
	s_waitcnt lgkmcnt(2)
	v_mfma_f32_32x32x16_bf16 v[16:31], v[92:95], v[100:103], v[16:31]
	s_waitcnt lgkmcnt(0)
	v_mfma_f32_32x32x16_bf16 v[0:15], v[96:99], v[100:103], v[0:15]
	ds_read_b64_tr_b16 v[92:93], v180 offset:43008
	ds_read_b64_tr_b16 v[94:95], v180 offset:43520
	ds_read_b64_tr_b16 v[96:97], v180 offset:47104
	ds_read_b64_tr_b16 v[98:99], v180 offset:47616
	s_waitcnt lgkmcnt(2)
	v_mfma_f32_32x32x16_bf16 v[16:31], v[92:95], v[80:83], v[16:31]
	s_waitcnt lgkmcnt(0)
	v_mfma_f32_32x32x16_bf16 v[0:15], v[96:99], v[80:83], v[0:15]
	ds_read_b64_tr_b16 v[80:81], v180 offset:44032
	ds_read_b64_tr_b16 v[82:83], v180 offset:44544
	ds_read_b64_tr_b16 v[92:93], v180 offset:48128
	ds_read_b64_tr_b16 v[94:95], v180 offset:48640
	s_waitcnt lgkmcnt(2)
	v_mfma_f32_32x32x16_bf16 v[16:31], v[80:83], v[88:91], v[16:31]
	s_waitcnt lgkmcnt(0)
	v_mfma_f32_32x32x16_bf16 v[0:15], v[92:95], v[88:91], v[0:15]
	v_add_f32_e32 v182, v84, v85
	v_add_f32_e32 v183, v86, v87
	v_add_f32_e32 v182, v182, v183
	v_add_f32_e32 v169, v169, v182
	s_waitcnt vmcnt(2)
	s_waitcnt lgkmcnt(0)
	s_barrier
	s_add_i32 s80, s80, 4
	s_cmp_lt_u32 s80, 60
	s_cbranch_scc1 .Lfa_g0_loop
	s_add_i32 m0, s40, 57344
	s_nop 0
	global_load_lds_dwordx4 v174, s[84:85]
	s_add_i32 m0, s41, 16384
	s_nop 0
	global_load_lds_dwordx4 v172, s[82:83]
	s_add_u32 s84, s84, 0x48000
	s_addc_u32 s85, s85, 0
	s_add_u32 s82, s82, 0x48000
	s_addc_u32 s83, s83, 0
	ds_read_b128 v[80:83], v179 offset:8192
	ds_read_b128 v[182:185], v179 offset:8704
	ds_read_b128 v[186:189], v179 offset:10240
	ds_read_b128 v[190:193], v179 offset:10752
	ds_read_b128 v[200:203], v179 offset:12288
	ds_read_b128 v[204:207], v179 offset:12800
	ds_read_b128 v[208:211], v179 offset:14336
	ds_read_b128 v[212:215], v179 offset:14848
	v_exp_f32_e32 v64, v64
	v_exp_f32_e32 v65, v65
	v_exp_f32_e32 v66, v66
	v_exp_f32_e32 v67, v67
	v_exp_f32_e32 v48, v48
	v_exp_f32_e32 v49, v49
	v_exp_f32_e32 v50, v50
	v_exp_f32_e32 v51, v51
	v_add_f32_e32 v84, v50, v66
	v_add_f32_e32 v85, v51, v67
	v_add_f32_e32 v86, v48, v64
	v_add_f32_e32 v87, v49, v65
	v_cvt_pk_bf16_f32 v64, v64, v65
	v_cvt_pk_bf16_f32 v65, v66, v67
	v_cvt_pk_bf16_f32 v48, v48, v49
	v_cvt_pk_bf16_f32 v49, v50, v51
	s_waitcnt lgkmcnt(7)
	v_mfma_f32_32x32x16_bf16 v[96:111], v[80:83], v[118:121], v[32:47]
	v_exp_f32_e32 v50, v68
	v_exp_f32_e32 v51, v69
	v_exp_f32_e32 v68, v70
	v_exp_f32_e32 v69, v71
	v_add_f32_e32 v70, v50, v86
	v_add_f32_e32 v71, v51, v87
	v_add_f32_e32 v181, v68, v84
	v_add_f32_e32 v228, v69, v85
	v_cvt_pk_bf16_f32 v66, v50, v51
	v_cvt_pk_bf16_f32 v67, v68, v69
	s_waitcnt lgkmcnt(6)
	v_mfma_f32_32x32x16_bf16 v[80:95], v[182:185], v[118:121], v[32:47]
	v_exp_f32_e32 v50, v52
	v_exp_f32_e32 v51, v53
	v_exp_f32_e32 v52, v54
	v_exp_f32_e32 v53, v55
	v_add_f32_e32 v54, v50, v70
	v_add_f32_e32 v55, v51, v71
	v_add_f32_e32 v68, v52, v181
	v_add_f32_e32 v69, v53, v228
	v_cvt_pk_bf16_f32 v50, v50, v51
	v_cvt_pk_bf16_f32 v51, v52, v53
	s_waitcnt lgkmcnt(5)
	v_mfma_f32_32x32x16_bf16 v[96:111], v[186:189], v[122:125], v[96:111]
	v_exp_f32_e32 v52, v72
	v_exp_f32_e32 v53, v73
	v_exp_f32_e32 v70, v74
	v_exp_f32_e32 v71, v75
	v_add_f32_e32 v54, v52, v54
	v_add_f32_e32 v55, v53, v55
	v_add_f32_e32 v72, v70, v68
	v_add_f32_e32 v73, v71, v69
	v_cvt_pk_bf16_f32 v68, v52, v53
	v_cvt_pk_bf16_f32 v69, v70, v71
	s_waitcnt lgkmcnt(4)
	v_mfma_f32_32x32x16_bf16 v[80:95], v[190:193], v[122:125], v[80:95]
	v_exp_f32_e32 v52, v56
	v_exp_f32_e32 v53, v57
	v_exp_f32_e32 v57, v58
	v_exp_f32_e32 v58, v59
	v_add_f32_e32 v54, v52, v54
	v_add_f32_e32 v55, v53, v55
	v_add_f32_e32 v59, v57, v72
	v_add_f32_e32 v70, v58, v73
	v_cvt_pk_bf16_f32 v56, v52, v53
	v_cvt_pk_bf16_f32 v57, v57, v58
	s_waitcnt lgkmcnt(3)
	v_mfma_f32_32x32x16_bf16 v[96:111], v[200:203], v[126:129], v[96:111]
	v_exp_f32_e32 v52, v76
	v_exp_f32_e32 v53, v77
	v_exp_f32_e32 v58, v78
	v_exp_f32_e32 v71, v79
	v_add_f32_e32 v54, v52, v54
	v_add_f32_e32 v55, v53, v55
	v_add_f32_e32 v59, v58, v59
	v_add_f32_e32 v72, v71, v70
	v_cvt_pk_bf16_f32 v70, v52, v53
	v_cvt_pk_bf16_f32 v71, v58, v71
	s_waitcnt lgkmcnt(2)
	v_mfma_f32_32x32x16_bf16 v[80:95], v[204:207], v[126:129], v[80:95]
	v_exp_f32_e32 v58, v60
	v_exp_f32_e32 v60, v61
	v_exp_f32_e32 v61, v62
	v_exp_f32_e32 v62, v63
	v_add_f32_e32 v52, v58, v54
	v_add_f32_e32 v53, v60, v55
	v_add_f32_e32 v54, v61, v59
	v_add_f32_e32 v55, v62, v72
	v_cvt_pk_bf16_f32 v58, v58, v60
	v_cvt_pk_bf16_f32 v59, v61, v62
	s_waitcnt lgkmcnt(1)
	v_mfma_f32_32x32x16_bf16 v[96:111], v[208:211], v[130:133], v[96:111]
	ds_read_b64_tr_b16 v[60:61], v180 offset:16384
	ds_read_b64_tr_b16 v[62:63], v180 offset:16896
	ds_read_b64_tr_b16 v[72:73], v180 offset:20480
	ds_read_b64_tr_b16 v[74:75], v180 offset:20992
	s_waitcnt lgkmcnt(4)
	v_mfma_f32_32x32x16_bf16 v[80:95], v[212:215], v[130:133], v[80:95]
	s_waitcnt lgkmcnt(2)
	v_mfma_f32_32x32x16_bf16 v[16:31], v[60:63], v[64:67], v[16:31]
	s_waitcnt lgkmcnt(0)
	v_mfma_f32_32x32x16_bf16 v[0:15], v[72:75], v[64:67], v[0:15]
	ds_read_b64_tr_b16 v[60:61], v180 offset:17408
	ds_read_b64_tr_b16 v[62:63], v180 offset:17920
	ds_read_b64_tr_b16 v[64:65], v180 offset:21504
	ds_read_b64_tr_b16 v[66:67], v180 offset:22016
	s_waitcnt lgkmcnt(2)
	v_mfma_f32_32x32x16_bf16 v[16:31], v[60:63], v[68:71], v[16:31]
	s_waitcnt lgkmcnt(0)
	v_mfma_f32_32x32x16_bf16 v[0:15], v[64:67], v[68:71], v[0:15]
	ds_read_b64_tr_b16 v[60:61], v180 offset:18432
	ds_read_b64_tr_b16 v[62:63], v180 offset:18944
	ds_read_b64_tr_b16 v[64:65], v180 offset:22528
	ds_read_b64_tr_b16 v[66:67], v180 offset:23040
	s_waitcnt lgkmcnt(2)
	v_mfma_f32_32x32x16_bf16 v[16:31], v[60:63], v[48:51], v[16:31]
	s_waitcnt lgkmcnt(0)
	v_mfma_f32_32x32x16_bf16 v[0:15], v[64:67], v[48:51], v[0:15]
	ds_read_b64_tr_b16 v[48:49], v180 offset:19456
	ds_read_b64_tr_b16 v[50:51], v180 offset:19968
	ds_read_b64_tr_b16 v[60:61], v180 offset:23552
	ds_read_b64_tr_b16 v[62:63], v180 offset:24064
	s_waitcnt lgkmcnt(2)
	v_mfma_f32_32x32x16_bf16 v[16:31], v[48:51], v[56:59], v[16:31]
	s_waitcnt lgkmcnt(0)
	v_mfma_f32_32x32x16_bf16 v[0:15], v[60:63], v[56:59], v[0:15]
	v_add_f32_e32 v182, v52, v53
	v_add_f32_e32 v183, v54, v55
	v_add_f32_e32 v182, v182, v183
	v_add_f32_e32 v169, v169, v182
	s_waitcnt vmcnt(2)
	s_waitcnt lgkmcnt(0)
	s_barrier
	s_add_i32 m0, s41, 24576
	s_nop 0
	global_load_lds_dwordx4 v172, s[82:83]
	s_add_u32 s84, s84, 0x48000
	s_addc_u32 s85, s85, 0
	s_add_u32 s82, s82, 0x48000
	s_addc_u32 s83, s83, 0
	ds_read_b128 v[182:185], v179 offset:49152
	ds_read_b128 v[186:189], v179 offset:49664
	ds_read_b128 v[190:193], v179 offset:51200
	ds_read_b128 v[200:203], v179 offset:51712
	ds_read_b128 v[204:207], v179 offset:53248
	ds_read_b128 v[208:211], v179 offset:53760
	ds_read_b128 v[212:215], v179 offset:55296
	ds_read_b128 v[146:149], v179 offset:55808
	v_exp_f32_e32 v64, v96
	v_exp_f32_e32 v65, v97
	v_exp_f32_e32 v66, v98
	v_exp_f32_e32 v67, v99
	v_cvt_pk_bf16_f32 v96, v64, v65
	v_cvt_pk_bf16_f32 v97, v66, v67
	v_exp_f32_e32 v68, v80
	v_exp_f32_e32 v69, v81
	v_exp_f32_e32 v70, v82
	v_exp_f32_e32 v71, v83
	v_cvt_pk_bf16_f32 v80, v68, v69
	v_cvt_pk_bf16_f32 v81, v70, v71
	v_add_f32_e32 v68, v68, v64
	v_add_f32_e32 v69, v69, v65
	v_add_f32_e32 v82, v70, v66
	v_add_f32_e32 v83, v71, v67
	v_exp_f32_e32 v98, v100
	v_exp_f32_e32 v99, v101
	v_exp_f32_e32 v100, v102
	v_exp_f32_e32 v101, v103
	v_add_f32_e32 v102, v98, v68
	v_add_f32_e32 v103, v99, v69
	s_waitcnt lgkmcnt(7)
	v_mfma_f32_32x32x16_bf16 v[64:79], v[182:185], v[118:121], v[32:47]
	v_add_f32_e32 v82, v100, v82
	v_add_f32_e32 v83, v101, v83
	v_cvt_pk_bf16_f32 v98, v98, v99
	v_cvt_pk_bf16_f32 v99, v100, v101
	s_waitcnt lgkmcnt(6)
	v_mfma_f32_32x32x16_bf16 v[48:63], v[186:189], v[118:121], v[32:47]
	v_exp_f32_e32 v84, v84
	v_exp_f32_e32 v85, v85
	v_exp_f32_e32 v86, v86
	v_exp_f32_e32 v87, v87
	v_add_f32_e32 v100, v84, v102
	v_add_f32_e32 v101, v85, v103
	v_add_f32_e32 v102, v86, v82
	v_add_f32_e32 v103, v87, v83
	v_cvt_pk_bf16_f32 v82, v84, v85
	v_cvt_pk_bf16_f32 v83, v86, v87
	s_waitcnt lgkmcnt(5)
	v_mfma_f32_32x32x16_bf16 v[64:79], v[190:193], v[122:125], v[64:79]
	v_exp_f32_e32 v84, v104
	v_exp_f32_e32 v85, v105
	v_exp_f32_e32 v86, v106
	v_exp_f32_e32 v87, v107
	v_add_f32_e32 v104, v84, v100
	v_add_f32_e32 v105, v85, v101
	v_add_f32_e32 v102, v86, v102
	v_add_f32_e32 v103, v87, v103
	v_cvt_pk_bf16_f32 v100, v84, v85
	v_cvt_pk_bf16_f32 v101, v86, v87
	s_waitcnt lgkmcnt(4)
	v_mfma_f32_32x32x16_bf16 v[48:63], v[200:203], v[122:125], v[48:63]
	v_exp_f32_e32 v84, v88
	v_exp_f32_e32 v85, v89
	v_exp_f32_e32 v86, v90
	v_exp_f32_e32 v87, v91
	v_add_f32_e32 v90, v84, v104
	v_add_f32_e32 v91, v85, v105
	v_add_f32_e32 v102, v86, v102
	v_add_f32_e32 v103, v87, v103
	v_cvt_pk_bf16_f32 v88, v84, v85
	v_cvt_pk_bf16_f32 v89, v86, v87
	s_waitcnt lgkmcnt(3)
	v_mfma_f32_32x32x16_bf16 v[64:79], v[204:207], v[126:129], v[64:79]
	v_exp_f32_e32 v84, v108
	v_exp_f32_e32 v85, v109
	v_exp_f32_e32 v86, v110
	v_exp_f32_e32 v87, v111
	v_add_f32_e32 v90, v84, v90
	v_add_f32_e32 v91, v85, v91
	v_add_f32_e32 v104, v86, v102
	v_add_f32_e32 v105, v87, v103
	v_cvt_pk_bf16_f32 v102, v84, v85
	v_cvt_pk_bf16_f32 v103, v86, v87
	s_waitcnt lgkmcnt(2)
	v_mfma_f32_32x32x16_bf16 v[48:63], v[208:211], v[126:129], v[48:63]
	v_exp_f32_e32 v92, v92
	v_exp_f32_e32 v93, v93
	v_exp_f32_e32 v94, v94
	v_exp_f32_e32 v95, v95
	v_add_f32_e32 v84, v92, v90
	v_add_f32_e32 v85, v93, v91
	v_add_f32_e32 v86, v94, v104
	v_add_f32_e32 v87, v95, v105
	v_cvt_pk_bf16_f32 v90, v92, v93
	v_cvt_pk_bf16_f32 v91, v94, v95
	s_waitcnt lgkmcnt(1)
	v_mfma_f32_32x32x16_bf16 v[64:79], v[212:215], v[130:133], v[64:79]
	ds_read_b64_tr_b16 v[92:93], v180 offset:24576
	ds_read_b64_tr_b16 v[94:95], v180 offset:25088
	ds_read_b64_tr_b16 v[104:105], v180 offset:28672
	ds_read_b64_tr_b16 v[106:107], v180 offset:29184
	s_waitcnt lgkmcnt(4)
	v_mfma_f32_32x32x16_bf16 v[48:63], v[146:149], v[130:133], v[48:63]
	s_waitcnt lgkmcnt(2)
	v_mfma_f32_32x32x16_bf16 v[16:31], v[92:95], v[96:99], v[16:31]
	s_waitcnt lgkmcnt(0)
	v_mfma_f32_32x32x16_bf16 v[0:15], v[104:107], v[96:99], v[0:15]
	ds_read_b64_tr_b16 v[92:93], v180 offset:25600
	ds_read_b64_tr_b16 v[94:95], v180 offset:26112
	ds_read_b64_tr_b16 v[96:97], v180 offset:29696
	ds_read_b64_tr_b16 v[98:99], v180 offset:30208
	s_waitcnt lgkmcnt(2)
	v_mfma_f32_32x32x16_bf16 v[16:31], v[92:95], v[100:103], v[16:31]
	s_waitcnt lgkmcnt(0)
	v_mfma_f32_32x32x16_bf16 v[0:15], v[96:99], v[100:103], v[0:15]
	ds_read_b64_tr_b16 v[92:93], v180 offset:26624
	ds_read_b64_tr_b16 v[94:95], v180 offset:27136
	ds_read_b64_tr_b16 v[96:97], v180 offset:30720
	ds_read_b64_tr_b16 v[98:99], v180 offset:31232
	s_waitcnt lgkmcnt(2)
	v_mfma_f32_32x32x16_bf16 v[16:31], v[92:95], v[80:83], v[16:31]
	s_waitcnt lgkmcnt(0)
	v_mfma_f32_32x32x16_bf16 v[0:15], v[96:99], v[80:83], v[0:15]
	ds_read_b64_tr_b16 v[80:81], v180 offset:27648
	ds_read_b64_tr_b16 v[82:83], v180 offset:28160
	ds_read_b64_tr_b16 v[92:93], v180 offset:31744
	ds_read_b64_tr_b16 v[94:95], v180 offset:32256
	s_waitcnt lgkmcnt(2)
	v_mfma_f32_32x32x16_bf16 v[16:31], v[80:83], v[88:91], v[16:31]
	s_waitcnt lgkmcnt(0)
	v_mfma_f32_32x32x16_bf16 v[0:15], v[92:95], v[88:91], v[0:15]
	v_add_f32_e32 v182, v84, v85
	v_add_f32_e32 v183, v86, v87
	v_add_f32_e32 v182, v182, v183
	v_add_f32_e32 v169, v169, v182
	s_waitcnt vmcnt(1)
	s_waitcnt lgkmcnt(0)
	s_barrier
	s_add_u32 s84, s84, 0x48000
	s_addc_u32 s85, s85, 0
	s_add_u32 s82, s82, 0x48000
	s_addc_u32 s83, s83, 0
	ds_read_b128 v[80:83], v179 offset:57344
	ds_read_b128 v[182:185], v179 offset:57856
	ds_read_b128 v[186:189], v179 offset:59392
	ds_read_b128 v[190:193], v179 offset:59904
	ds_read_b128 v[200:203], v179 offset:61440
	ds_read_b128 v[204:207], v179 offset:61952
	ds_read_b128 v[208:211], v179 offset:63488
	ds_read_b128 v[212:215], v179 offset:64000
	v_exp_f32_e32 v64, v64
	v_exp_f32_e32 v65, v65
	v_exp_f32_e32 v66, v66
	v_exp_f32_e32 v67, v67
	v_exp_f32_e32 v48, v48
	v_exp_f32_e32 v49, v49
	v_exp_f32_e32 v50, v50
	v_exp_f32_e32 v51, v51
	v_add_f32_e32 v84, v50, v66
	v_add_f32_e32 v85, v51, v67
	v_add_f32_e32 v86, v48, v64
	v_add_f32_e32 v87, v49, v65
	v_cvt_pk_bf16_f32 v64, v64, v65
	v_cvt_pk_bf16_f32 v65, v66, v67
	v_cvt_pk_bf16_f32 v48, v48, v49
	v_cvt_pk_bf16_f32 v49, v50, v51
	s_waitcnt lgkmcnt(7)
	v_mfma_f32_32x32x16_bf16 v[96:111], v[80:83], v[118:121], v[32:47]
	v_exp_f32_e32 v50, v68
	v_exp_f32_e32 v51, v69
	v_exp_f32_e32 v68, v70
	v_exp_f32_e32 v69, v71
	v_add_f32_e32 v70, v50, v86
	v_add_f32_e32 v71, v51, v87
	v_add_f32_e32 v181, v68, v84
	v_add_f32_e32 v228, v69, v85
	v_cvt_pk_bf16_f32 v66, v50, v51
	v_cvt_pk_bf16_f32 v67, v68, v69
	s_waitcnt lgkmcnt(6)
	v_mfma_f32_32x32x16_bf16 v[80:95], v[182:185], v[118:121], v[32:47]
	v_exp_f32_e32 v50, v52
	v_exp_f32_e32 v51, v53
	v_exp_f32_e32 v52, v54
	v_exp_f32_e32 v53, v55
	v_add_f32_e32 v54, v50, v70
	v_add_f32_e32 v55, v51, v71
	v_add_f32_e32 v68, v52, v181
	v_add_f32_e32 v69, v53, v228
	v_cvt_pk_bf16_f32 v50, v50, v51
	v_cvt_pk_bf16_f32 v51, v52, v53
	s_waitcnt lgkmcnt(5)
	v_mfma_f32_32x32x16_bf16 v[96:111], v[186:189], v[122:125], v[96:111]
	v_exp_f32_e32 v52, v72
	v_exp_f32_e32 v53, v73
	v_exp_f32_e32 v70, v74
	v_exp_f32_e32 v71, v75
	v_add_f32_e32 v54, v52, v54
	v_add_f32_e32 v55, v53, v55
	v_add_f32_e32 v72, v70, v68
	v_add_f32_e32 v73, v71, v69
	v_cvt_pk_bf16_f32 v68, v52, v53
	v_cvt_pk_bf16_f32 v69, v70, v71
	s_waitcnt lgkmcnt(4)
	v_mfma_f32_32x32x16_bf16 v[80:95], v[190:193], v[122:125], v[80:95]
	v_exp_f32_e32 v52, v56
	v_exp_f32_e32 v53, v57
	v_exp_f32_e32 v57, v58
	v_exp_f32_e32 v58, v59
	v_add_f32_e32 v54, v52, v54
	v_add_f32_e32 v55, v53, v55
	v_add_f32_e32 v59, v57, v72
	v_add_f32_e32 v70, v58, v73
	v_cvt_pk_bf16_f32 v56, v52, v53
	v_cvt_pk_bf16_f32 v57, v57, v58
	s_waitcnt lgkmcnt(3)
	v_mfma_f32_32x32x16_bf16 v[96:111], v[200:203], v[126:129], v[96:111]
	v_exp_f32_e32 v52, v76
	v_exp_f32_e32 v53, v77
	v_exp_f32_e32 v58, v78
	v_exp_f32_e32 v71, v79
	v_add_f32_e32 v54, v52, v54
	v_add_f32_e32 v55, v53, v55
	v_add_f32_e32 v59, v58, v59
	v_add_f32_e32 v72, v71, v70
	v_cvt_pk_bf16_f32 v70, v52, v53
	v_cvt_pk_bf16_f32 v71, v58, v71
	s_waitcnt lgkmcnt(2)
	v_mfma_f32_32x32x16_bf16 v[80:95], v[204:207], v[126:129], v[80:95]
	v_exp_f32_e32 v58, v60
	v_exp_f32_e32 v60, v61
	v_exp_f32_e32 v61, v62
	v_exp_f32_e32 v62, v63
	v_add_f32_e32 v52, v58, v54
	v_add_f32_e32 v53, v60, v55
	v_add_f32_e32 v54, v61, v59
	v_add_f32_e32 v55, v62, v72
	v_cvt_pk_bf16_f32 v58, v58, v60
	v_cvt_pk_bf16_f32 v59, v61, v62
	s_waitcnt lgkmcnt(1)
	v_mfma_f32_32x32x16_bf16 v[96:111], v[208:211], v[130:133], v[96:111]
	ds_read_b64_tr_b16 v[60:61], v180 offset:32768
	ds_read_b64_tr_b16 v[62:63], v180 offset:33280
	ds_read_b64_tr_b16 v[72:73], v180 offset:36864
	ds_read_b64_tr_b16 v[74:75], v180 offset:37376
	s_waitcnt lgkmcnt(4)
	v_mfma_f32_32x32x16_bf16 v[80:95], v[212:215], v[130:133], v[80:95]
	s_waitcnt lgkmcnt(2)
	v_mfma_f32_32x32x16_bf16 v[16:31], v[60:63], v[64:67], v[16:31]
	s_waitcnt lgkmcnt(0)
	v_mfma_f32_32x32x16_bf16 v[0:15], v[72:75], v[64:67], v[0:15]
	ds_read_b64_tr_b16 v[60:61], v180 offset:33792
	ds_read_b64_tr_b16 v[62:63], v180 offset:34304
	ds_read_b64_tr_b16 v[64:65], v180 offset:37888
	ds_read_b64_tr_b16 v[66:67], v180 offset:38400
	s_waitcnt lgkmcnt(2)
	v_mfma_f32_32x32x16_bf16 v[16:31], v[60:63], v[68:71], v[16:31]
	s_waitcnt lgkmcnt(0)
	v_mfma_f32_32x32x16_bf16 v[0:15], v[64:67], v[68:71], v[0:15]
	ds_read_b64_tr_b16 v[60:61], v180 offset:34816
	ds_read_b64_tr_b16 v[62:63], v180 offset:35328
	ds_read_b64_tr_b16 v[64:65], v180 offset:38912
	ds_read_b64_tr_b16 v[66:67], v180 offset:39424
	s_waitcnt lgkmcnt(2)
	v_mfma_f32_32x32x16_bf16 v[16:31], v[60:63], v[48:51], v[16:31]
	s_waitcnt lgkmcnt(0)
	v_mfma_f32_32x32x16_bf16 v[0:15], v[64:67], v[48:51], v[0:15]
	ds_read_b64_tr_b16 v[48:49], v180 offset:35840
	ds_read_b64_tr_b16 v[50:51], v180 offset:36352
	ds_read_b64_tr_b16 v[60:61], v180 offset:39936
	ds_read_b64_tr_b16 v[62:63], v180 offset:40448
	s_waitcnt lgkmcnt(2)
	v_mfma_f32_32x32x16_bf16 v[16:31], v[48:51], v[56:59], v[16:31]
	s_waitcnt lgkmcnt(0)
	v_mfma_f32_32x32x16_bf16 v[0:15], v[60:63], v[56:59], v[0:15]
	v_add_f32_e32 v182, v52, v53
	v_add_f32_e32 v183, v54, v55
	v_add_f32_e32 v182, v182, v183
	v_add_f32_e32 v169, v169, v182
	s_waitcnt vmcnt(0)
	s_waitcnt lgkmcnt(0)
	s_barrier
; __device__ __forceinline__ void attn_unit(LAS unsigned char* lds, bf16_t* P, const float* qgain, const float* rope, int s, int h, int qb, int lane, int wid, bool dry) {
;     ...
;     const bf16_t* ksrc = P + (rowbase + lane) * EVEN_IN + 1536 + kvh * 64 + wid * 8;
;     const bf16_t* vsrc = P + (rowbase + 16 * (wid & 3) + (lane >> 2)) * EVEN_IN + 1664 + kvh * 64 + (wid >> 2) * 32 + (lane & 3) * 8;
;     const int kdst = wid * 1024 + lane * 16;
;     const int vdst = 16384 + (wid >> 2) * 4096 + (16 * (wid & 3) + (lane >> 2)) * 64 + (lane & 3) * 16;
	s_add_u32 s84, s84, 0x48000
	s_addc_u32 s85, s85, 0
	s_add_u32 s82, s82, 0x48000
	s_addc_u32 s83, s83, 0
	v_exp_f32_e32 v64, v96
	v_exp_f32_e32 v65, v97
	v_exp_f32_e32 v66, v98
	v_exp_f32_e32 v67, v99
	v_cvt_pk_bf16_f32 v96, v64, v65
	v_cvt_pk_bf16_f32 v97, v66, v67
	v_exp_f32_e32 v68, v80
	v_exp_f32_e32 v69, v81
	v_exp_f32_e32 v70, v82
	v_exp_f32_e32 v71, v83
	v_cvt_pk_bf16_f32 v80, v68, v69
	v_cvt_pk_bf16_f32 v81, v70, v71
	v_add_f32_e32 v68, v68, v64
	v_add_f32_e32 v69, v69, v65
	v_add_f32_e32 v82, v70, v66
	v_add_f32_e32 v83, v71, v67
	v_exp_f32_e32 v98, v100
	v_exp_f32_e32 v99, v101
	v_exp_f32_e32 v100, v102
	v_exp_f32_e32 v101, v103
	v_add_f32_e32 v102, v98, v68
	v_add_f32_e32 v103, v99, v69
	v_add_f32_e32 v82, v100, v82
	v_add_f32_e32 v83, v101, v83
	v_cvt_pk_bf16_f32 v98, v98, v99
	v_cvt_pk_bf16_f32 v99, v100, v101
	v_exp_f32_e32 v84, v84
	v_exp_f32_e32 v85, v85
	v_exp_f32_e32 v86, v86
	v_exp_f32_e32 v87, v87
	v_add_f32_e32 v100, v84, v102
	v_add_f32_e32 v101, v85, v103
	v_add_f32_e32 v102, v86, v82
	v_add_f32_e32 v103, v87, v83
	v_cvt_pk_bf16_f32 v82, v84, v85
	v_cvt_pk_bf16_f32 v83, v86, v87
	v_exp_f32_e32 v84, v104
	v_exp_f32_e32 v85, v105
	v_exp_f32_e32 v86, v106
	v_exp_f32_e32 v87, v107
	v_add_f32_e32 v104, v84, v100
	v_add_f32_e32 v105, v85, v101
	v_add_f32_e32 v102, v86, v102
	v_add_f32_e32 v103, v87, v103
	v_cvt_pk_bf16_f32 v100, v84, v85
	v_cvt_pk_bf16_f32 v101, v86, v87
	v_exp_f32_e32 v84, v88
	v_exp_f32_e32 v85, v89
	v_exp_f32_e32 v86, v90
	v_exp_f32_e32 v87, v91
	v_add_f32_e32 v90, v84, v104
	v_add_f32_e32 v91, v85, v105
	v_add_f32_e32 v102, v86, v102
	v_add_f32_e32 v103, v87, v103
	v_cvt_pk_bf16_f32 v88, v84, v85
	v_cvt_pk_bf16_f32 v89, v86, v87
	v_exp_f32_e32 v84, v108
	v_exp_f32_e32 v85, v109
	v_exp_f32_e32 v86, v110
	v_exp_f32_e32 v87, v111
	v_add_f32_e32 v90, v84, v90
	v_add_f32_e32 v91, v85, v91
	v_add_f32_e32 v104, v86, v102
	v_add_f32_e32 v105, v87, v103
	v_cvt_pk_bf16_f32 v102, v84, v85
	v_cvt_pk_bf16_f32 v103, v86, v87
	v_exp_f32_e32 v92, v92
	v_exp_f32_e32 v93, v93
	v_exp_f32_e32 v94, v94
	v_exp_f32_e32 v95, v95
	v_add_f32_e32 v84, v92, v90
	v_add_f32_e32 v85, v93, v91
	v_add_f32_e32 v86, v94, v104
	v_add_f32_e32 v87, v95, v105
	v_cvt_pk_bf16_f32 v90, v92, v93
	v_cvt_pk_bf16_f32 v91, v94, v95
	ds_read_b64_tr_b16 v[92:93], v180 offset:40960
	ds_read_b64_tr_b16 v[94:95], v180 offset:41472
	ds_read_b64_tr_b16 v[104:105], v180 offset:45056
	ds_read_b64_tr_b16 v[106:107], v180 offset:45568
	s_waitcnt lgkmcnt(2)
	v_mfma_f32_32x32x16_bf16 v[16:31], v[92:95], v[96:99], v[16:31]
	s_waitcnt lgkmcnt(0)
	v_mfma_f32_32x32x16_bf16 v[0:15], v[104:107], v[96:99], v[0:15]
	ds_read_b64_tr_b16 v[92:93], v180 offset:41984
	ds_read_b64_tr_b16 v[94:95], v180 offset:42496
	ds_read_b64_tr_b16 v[96:97], v180 offset:46080
	ds_read_b64_tr_b16 v[98:99], v180 offset:46592
	s_waitcnt lgkmcnt(2)
	v_mfma_f32_32x32x16_bf16 v[16:31], v[92:95], v[100:103], v[16:31]
	s_waitcnt lgkmcnt(0)
	v_mfma_f32_32x32x16_bf16 v[0:15], v[96:99], v[100:103], v[0:15]
	ds_read_b64_tr_b16 v[92:93], v180 offset:43008
	ds_read_b64_tr_b16 v[94:95], v180 offset:43520
	ds_read_b64_tr_b16 v[96:97], v180 offset:47104
	ds_read_b64_tr_b16 v[98:99], v180 offset:47616
	s_waitcnt lgkmcnt(2)
	v_mfma_f32_32x32x16_bf16 v[16:31], v[92:95], v[80:83], v[16:31]
	s_waitcnt lgkmcnt(0)
	v_mfma_f32_32x32x16_bf16 v[0:15], v[96:99], v[80:83], v[0:15]
	ds_read_b64_tr_b16 v[80:81], v180 offset:44032
	ds_read_b64_tr_b16 v[82:83], v180 offset:44544
	ds_read_b64_tr_b16 v[92:93], v180 offset:48128
	ds_read_b64_tr_b16 v[94:95], v180 offset:48640
	s_waitcnt lgkmcnt(2)
	v_mfma_f32_32x32x16_bf16 v[16:31], v[80:83], v[88:91], v[16:31]
	s_waitcnt lgkmcnt(0)
	v_mfma_f32_32x32x16_bf16 v[0:15], v[92:95], v[88:91], v[0:15]
	v_add_f32_e32 v182, v84, v85
	v_add_f32_e32 v183, v86, v87
	v_add_f32_e32 v182, v182, v183
	v_add_f32_e32 v169, v169, v182
	s_waitcnt lgkmcnt(0)
	s_barrier
	s_branch .LBB0_62
.Lfa_g1_entry:
	v_lshl_add_u64 v[146:147], v[174:175], 0, s[46:47]
	v_lshl_add_u64 v[148:149], v[172:173], 0, s[46:47]
	s_nop 0
	v_readfirstlane_b32 s84, v146
	v_readfirstlane_b32 s85, v147
	v_readfirstlane_b32 s82, v148
	v_readfirstlane_b32 s83, v149
	s_nop 3
	v_subrev_u32_e32 v174, s84, v146
	v_subrev_u32_e32 v172, s82, v148
	s_add_u32 s84, s84, 0x88d8c00
	s_addc_u32 s85, s85, 0
	s_add_u32 s82, s82, 0x8890d00
	s_addc_u32 s83, s83, 0
	s_nop 4
	s_lshl_b32 s40, s38, 10
	s_lshr_b32 s41, s38, 2
	s_lshl_b32 s41, s41, 12
	s_and_b32 s39, s38, 3
	s_lshl_b32 s39, s39, 10
	s_add_i32 s41, s41, s39
	s_add_i32 s41, s41, 16384
	s_waitcnt vmcnt(0)
	ds_write_b128 v177, v[134:137] offset:49152
	ds_write_b128 v178, v[138:141] offset:24576
	s_add_i32 m0, s40, 57344
	s_nop 0
	global_load_lds_dwordx4 v174, s[84:85]
	s_add_i32 m0, s41, 16384
	s_nop 0
	global_load_lds_dwordx4 v172, s[82:83]
	s_add_u32 s84, s84, 0x48000
	s_addc_u32 s85, s85, 0
	s_add_u32 s82, s82, 0x48000
	s_addc_u32 s83, s83, 0
	ds_read_b128 v[80:83], v179 offset:8192
	ds_read_b128 v[182:185], v179 offset:8704
	ds_read_b128 v[186:189], v179 offset:10240
	ds_read_b128 v[190:193], v179 offset:10752
	ds_read_b128 v[200:203], v179 offset:12288
	ds_read_b128 v[204:207], v179 offset:12800
	ds_read_b128 v[208:211], v179 offset:14336
	ds_read_b128 v[212:215], v179 offset:14848
	v_exp_f32_e32 v64, v64
	v_exp_f32_e32 v65, v65
	v_exp_f32_e32 v66, v66
	v_exp_f32_e32 v67, v67
	v_exp_f32_e32 v48, v48
	v_exp_f32_e32 v49, v49
	v_exp_f32_e32 v50, v50
	v_exp_f32_e32 v51, v51
	v_add_f32_e32 v84, v50, v66
	v_add_f32_e32 v85, v51, v67
	v_add_f32_e32 v86, v48, v64
	v_add_f32_e32 v87, v49, v65
	v_cvt_pk_bf16_f32 v64, v64, v65
	v_cvt_pk_bf16_f32 v65, v66, v67
	v_cvt_pk_bf16_f32 v48, v48, v49
	v_cvt_pk_bf16_f32 v49, v50, v51
	s_waitcnt lgkmcnt(7)
	v_mfma_f32_32x32x16_bf16 v[96:111], v[80:83], v[118:121], v[32:47]
	v_exp_f32_e32 v50, v68
	v_exp_f32_e32 v51, v69
	v_exp_f32_e32 v68, v70
	v_exp_f32_e32 v69, v71
	v_add_f32_e32 v70, v50, v86
	v_add_f32_e32 v71, v51, v87
	v_add_f32_e32 v181, v68, v84
	v_add_f32_e32 v228, v69, v85
	v_cvt_pk_bf16_f32 v66, v50, v51
	v_cvt_pk_bf16_f32 v67, v68, v69
	s_waitcnt lgkmcnt(6)
	v_mfma_f32_32x32x16_bf16 v[80:95], v[182:185], v[118:121], v[32:47]
	v_exp_f32_e32 v50, v52
	v_exp_f32_e32 v51, v53
	v_exp_f32_e32 v52, v54
	v_exp_f32_e32 v53, v55
	v_add_f32_e32 v54, v50, v70
	v_add_f32_e32 v55, v51, v71
	v_add_f32_e32 v68, v52, v181
	v_add_f32_e32 v69, v53, v228
	v_cvt_pk_bf16_f32 v50, v50, v51
	v_cvt_pk_bf16_f32 v51, v52, v53
	s_waitcnt lgkmcnt(5)
	v_mfma_f32_32x32x16_bf16 v[96:111], v[186:189], v[122:125], v[96:111]
	v_exp_f32_e32 v52, v72
	v_exp_f32_e32 v53, v73
	v_exp_f32_e32 v70, v74
	v_exp_f32_e32 v71, v75
	v_add_f32_e32 v54, v52, v54
	v_add_f32_e32 v55, v53, v55
	v_add_f32_e32 v72, v70, v68
	v_add_f32_e32 v73, v71, v69
	v_cvt_pk_bf16_f32 v68, v52, v53
	v_cvt_pk_bf16_f32 v69, v70, v71
	s_waitcnt lgkmcnt(4)
	v_mfma_f32_32x32x16_bf16 v[80:95], v[190:193], v[122:125], v[80:95]
	v_exp_f32_e32 v52, v56
	v_exp_f32_e32 v53, v57
	v_exp_f32_e32 v57, v58
	v_exp_f32_e32 v58, v59
	v_add_f32_e32 v54, v52, v54
	v_add_f32_e32 v55, v53, v55
	v_add_f32_e32 v59, v57, v72
	v_add_f32_e32 v70, v58, v73
	v_cvt_pk_bf16_f32 v56, v52, v53
	v_cvt_pk_bf16_f32 v57, v57, v58
	s_waitcnt lgkmcnt(3)
	v_mfma_f32_32x32x16_bf16 v[96:111], v[200:203], v[126:129], v[96:111]
	v_exp_f32_e32 v52, v76
	v_exp_f32_e32 v53, v77
	v_exp_f32_e32 v58, v78
	v_exp_f32_e32 v71, v79
	v_add_f32_e32 v54, v52, v54
	v_add_f32_e32 v55, v53, v55
	v_add_f32_e32 v59, v58, v59
	v_add_f32_e32 v72, v71, v70
	v_cvt_pk_bf16_f32 v70, v52, v53
	v_cvt_pk_bf16_f32 v71, v58, v71
	s_waitcnt lgkmcnt(2)
	v_mfma_f32_32x32x16_bf16 v[80:95], v[204:207], v[126:129], v[80:95]
	v_exp_f32_e32 v58, v60
	v_exp_f32_e32 v60, v61
	v_exp_f32_e32 v61, v62
	v_exp_f32_e32 v62, v63
	v_add_f32_e32 v52, v58, v54
	v_add_f32_e32 v53, v60, v55
	v_add_f32_e32 v54, v61, v59
	v_add_f32_e32 v55, v62, v72
	v_cvt_pk_bf16_f32 v58, v58, v60
	v_cvt_pk_bf16_f32 v59, v61, v62
	s_waitcnt lgkmcnt(1)
	v_mfma_f32_32x32x16_bf16 v[96:111], v[208:211], v[130:133], v[96:111]
	s_waitcnt lgkmcnt(0)
	v_mfma_f32_32x32x16_bf16 v[80:95], v[212:215], v[130:133], v[80:95]
	v_add_f32_e32 v182, v52, v53
	v_add_f32_e32 v183, v54, v55
	v_add_f32_e32 v182, v182, v183
	v_add_f32_e32 v169, v169, v182
	s_waitcnt vmcnt(2)
	s_waitcnt lgkmcnt(0)
	s_barrier
	s_add_i32 m0, s40, 0
	s_nop 0
	global_load_lds_dwordx4 v174, s[84:85]
	s_add_i32 m0, s41, 24576
	s_nop 0
	global_load_lds_dwordx4 v172, s[82:83]
	s_add_u32 s84, s84, 0x48000
	s_addc_u32 s85, s85, 0
	s_add_u32 s82, s82, 0x48000
	s_addc_u32 s83, s83, 0
	ds_read_b64_tr_b16 v[60:61], v180 offset:16384
	ds_read_b64_tr_b16 v[62:63], v180 offset:16896
	ds_read_b64_tr_b16 v[72:73], v180 offset:20480
	ds_read_b64_tr_b16 v[74:75], v180 offset:20992
	s_waitcnt lgkmcnt(2)
	v_mfma_f32_32x32x16_bf16 v[16:31], v[60:63], v[64:67], v[16:31]
	s_waitcnt lgkmcnt(0)
	v_mfma_f32_32x32x16_bf16 v[0:15], v[72:75], v[64:67], v[0:15]
	ds_read_b64_tr_b16 v[60:61], v180 offset:17408
	ds_read_b64_tr_b16 v[62:63], v180 offset:17920
	ds_read_b64_tr_b16 v[64:65], v180 offset:21504
	ds_read_b64_tr_b16 v[66:67], v180 offset:22016
	s_waitcnt lgkmcnt(2)
	v_mfma_f32_32x32x16_bf16 v[16:31], v[60:63], v[68:71], v[16:31]
	s_waitcnt lgkmcnt(0)
	v_mfma_f32_32x32x16_bf16 v[0:15], v[64:67], v[68:71], v[0:15]
	ds_read_b64_tr_b16 v[60:61], v180 offset:18432
	ds_read_b64_tr_b16 v[62:63], v180 offset:18944
	ds_read_b64_tr_b16 v[64:65], v180 offset:22528
	ds_read_b64_tr_b16 v[66:67], v180 offset:23040
	s_waitcnt lgkmcnt(2)
	v_mfma_f32_32x32x16_bf16 v[16:31], v[60:63], v[48:51], v[16:31]
	s_waitcnt lgkmcnt(0)
	v_mfma_f32_32x32x16_bf16 v[0:15], v[64:67], v[48:51], v[0:15]
	ds_read_b64_tr_b16 v[48:49], v180 offset:19456
	ds_read_b64_tr_b16 v[50:51], v180 offset:19968
	ds_read_b64_tr_b16 v[60:61], v180 offset:23552
	ds_read_b64_tr_b16 v[62:63], v180 offset:24064
	s_waitcnt lgkmcnt(2)
	v_mfma_f32_32x32x16_bf16 v[16:31], v[48:51], v[56:59], v[16:31]
	s_waitcnt lgkmcnt(0)
	v_mfma_f32_32x32x16_bf16 v[0:15], v[60:63], v[56:59], v[0:15]
	ds_read_b128 v[182:185], v179 offset:49152
	ds_read_b128 v[186:189], v179 offset:49664
	ds_read_b128 v[190:193], v179 offset:51200
	ds_read_b128 v[200:203], v179 offset:51712
	ds_read_b128 v[204:207], v179 offset:53248
	ds_read_b128 v[208:211], v179 offset:53760
	ds_read_b128 v[212:215], v179 offset:55296
	ds_read_b128 v[146:149], v179 offset:55808
	v_exp_f32_e32 v64, v96
	v_exp_f32_e32 v65, v97
	v_exp_f32_e32 v66, v98
	v_exp_f32_e32 v67, v99
	v_cvt_pk_bf16_f32 v96, v64, v65
	v_cvt_pk_bf16_f32 v97, v66, v67
	v_exp_f32_e32 v68, v80
	v_exp_f32_e32 v69, v81
	v_exp_f32_e32 v70, v82
	v_exp_f32_e32 v71, v83
	v_cvt_pk_bf16_f32 v80, v68, v69
	v_cvt_pk_bf16_f32 v81, v70, v71
	v_add_f32_e32 v68, v68, v64
	v_add_f32_e32 v69, v69, v65
	v_add_f32_e32 v82, v70, v66
	v_add_f32_e32 v83, v71, v67
	v_exp_f32_e32 v98, v100
	v_exp_f32_e32 v99, v101
	v_exp_f32_e32 v100, v102
	v_exp_f32_e32 v101, v103
	v_add_f32_e32 v102, v98, v68
	v_add_f32_e32 v103, v99, v69
	s_waitcnt lgkmcnt(7)
	v_mfma_f32_32x32x16_bf16 v[64:79], v[182:185], v[118:121], v[32:47]
	v_add_f32_e32 v82, v100, v82
	v_add_f32_e32 v83, v101, v83
	v_cvt_pk_bf16_f32 v98, v98, v99
	v_cvt_pk_bf16_f32 v99, v100, v101
	s_waitcnt lgkmcnt(6)
	v_mfma_f32_32x32x16_bf16 v[48:63], v[186:189], v[118:121], v[32:47]
	v_exp_f32_e32 v84, v84
	v_exp_f32_e32 v85, v85
	v_exp_f32_e32 v86, v86
	v_exp_f32_e32 v87, v87
	v_add_f32_e32 v100, v84, v102
	v_add_f32_e32 v101, v85, v103
	v_add_f32_e32 v102, v86, v82
	v_add_f32_e32 v103, v87, v83
	v_cvt_pk_bf16_f32 v82, v84, v85
	v_cvt_pk_bf16_f32 v83, v86, v87
	s_waitcnt lgkmcnt(5)
	v_mfma_f32_32x32x16_bf16 v[64:79], v[190:193], v[122:125], v[64:79]
	v_exp_f32_e32 v84, v104
	v_exp_f32_e32 v85, v105
	v_exp_f32_e32 v86, v106
	v_exp_f32_e32 v87, v107
	v_add_f32_e32 v104, v84, v100
	v_add_f32_e32 v105, v85, v101
	v_add_f32_e32 v102, v86, v102
	v_add_f32_e32 v103, v87, v103
	v_cvt_pk_bf16_f32 v100, v84, v85
	v_cvt_pk_bf16_f32 v101, v86, v87
	s_waitcnt lgkmcnt(4)
	v_mfma_f32_32x32x16_bf16 v[48:63], v[200:203], v[122:125], v[48:63]
	v_exp_f32_e32 v84, v88
	v_exp_f32_e32 v85, v89
	v_exp_f32_e32 v86, v90
	v_exp_f32_e32 v87, v91
	v_add_f32_e32 v90, v84, v104
	v_add_f32_e32 v91, v85, v105
	v_add_f32_e32 v102, v86, v102
	v_add_f32_e32 v103, v87, v103
	v_cvt_pk_bf16_f32 v88, v84, v85
	v_cvt_pk_bf16_f32 v89, v86, v87
	s_waitcnt lgkmcnt(3)
	v_mfma_f32_32x32x16_bf16 v[64:79], v[204:207], v[126:129], v[64:79]
	v_exp_f32_e32 v84, v108
	v_exp_f32_e32 v85, v109
	v_exp_f32_e32 v86, v110
	v_exp_f32_e32 v87, v111
	v_add_f32_e32 v90, v84, v90
	v_add_f32_e32 v91, v85, v91
	v_add_f32_e32 v104, v86, v102
	v_add_f32_e32 v105, v87, v103
	v_cvt_pk_bf16_f32 v102, v84, v85
	v_cvt_pk_bf16_f32 v103, v86, v87
	s_waitcnt lgkmcnt(2)
	v_mfma_f32_32x32x16_bf16 v[48:63], v[208:211], v[126:129], v[48:63]
	v_exp_f32_e32 v92, v92
	v_exp_f32_e32 v93, v93
	v_exp_f32_e32 v94, v94
	v_exp_f32_e32 v95, v95
	v_add_f32_e32 v84, v92, v90
	v_add_f32_e32 v85, v93, v91
	v_add_f32_e32 v86, v94, v104
	v_add_f32_e32 v87, v95, v105
	v_cvt_pk_bf16_f32 v90, v92, v93
	v_cvt_pk_bf16_f32 v91, v94, v95
	s_waitcnt lgkmcnt(1)
	v_mfma_f32_32x32x16_bf16 v[64:79], v[212:215], v[130:133], v[64:79]
	s_waitcnt lgkmcnt(0)
	v_mfma_f32_32x32x16_bf16 v[48:63], v[146:149], v[130:133], v[48:63]
	v_add_f32_e32 v182, v84, v85
	v_add_f32_e32 v183, v86, v87
	v_add_f32_e32 v182, v182, v183
	v_add_f32_e32 v169, v169, v182
	s_waitcnt vmcnt(2)
	s_waitcnt lgkmcnt(0)
	s_barrier
	s_add_i32 m0, s40, 8192
	s_nop 0
	global_load_lds_dwordx4 v174, s[84:85]
	s_add_i32 m0, s41, 0
	s_nop 0
	global_load_lds_dwordx4 v172, s[82:83]
	s_add_u32 s84, s84, 0x48000
	s_addc_u32 s85, s85, 0
	s_add_u32 s82, s82, 0x48000
	s_addc_u32 s83, s83, 0
	ds_read_b64_tr_b16 v[92:93], v180 offset:24576
	ds_read_b64_tr_b16 v[94:95], v180 offset:25088
	ds_read_b64_tr_b16 v[104:105], v180 offset:28672
	ds_read_b64_tr_b16 v[106:107], v180 offset:29184
	s_waitcnt lgkmcnt(2)
	v_mfma_f32_32x32x16_bf16 v[16:31], v[92:95], v[96:99], v[16:31]
	s_waitcnt lgkmcnt(0)
	v_mfma_f32_32x32x16_bf16 v[0:15], v[104:107], v[96:99], v[0:15]
	ds_read_b64_tr_b16 v[92:93], v180 offset:25600
	ds_read_b64_tr_b16 v[94:95], v180 offset:26112
	ds_read_b64_tr_b16 v[96:97], v180 offset:29696
	ds_read_b64_tr_b16 v[98:99], v180 offset:30208
	s_waitcnt lgkmcnt(2)
	v_mfma_f32_32x32x16_bf16 v[16:31], v[92:95], v[100:103], v[16:31]
	s_waitcnt lgkmcnt(0)
	v_mfma_f32_32x32x16_bf16 v[0:15], v[96:99], v[100:103], v[0:15]
	ds_read_b64_tr_b16 v[92:93], v180 offset:26624
	ds_read_b64_tr_b16 v[94:95], v180 offset:27136
	ds_read_b64_tr_b16 v[96:97], v180 offset:30720
	ds_read_b64_tr_b16 v[98:99], v180 offset:31232
	s_waitcnt lgkmcnt(2)
	v_mfma_f32_32x32x16_bf16 v[16:31], v[92:95], v[80:83], v[16:31]
	s_waitcnt lgkmcnt(0)
	v_mfma_f32_32x32x16_bf16 v[0:15], v[96:99], v[80:83], v[0:15]
	ds_read_b64_tr_b16 v[80:81], v180 offset:27648
	ds_read_b64_tr_b16 v[82:83], v180 offset:28160
	ds_read_b64_tr_b16 v[92:93], v180 offset:31744
	ds_read_b64_tr_b16 v[94:95], v180 offset:32256
	s_waitcnt lgkmcnt(2)
	v_mfma_f32_32x32x16_bf16 v[16:31], v[80:83], v[88:91], v[16:31]
	s_waitcnt lgkmcnt(0)
	v_mfma_f32_32x32x16_bf16 v[0:15], v[92:95], v[88:91], v[0:15]
	ds_read_b128 v[80:83], v179 offset:57344
	ds_read_b128 v[182:185], v179 offset:57856
	ds_read_b128 v[186:189], v179 offset:59392
	ds_read_b128 v[190:193], v179 offset:59904
	ds_read_b128 v[200:203], v179 offset:61440
	ds_read_b128 v[204:207], v179 offset:61952
	ds_read_b128 v[208:211], v179 offset:63488
	ds_read_b128 v[212:215], v179 offset:64000
	v_exp_f32_e32 v64, v64
	v_exp_f32_e32 v65, v65
	v_exp_f32_e32 v66, v66
	v_exp_f32_e32 v67, v67
	v_exp_f32_e32 v48, v48
	v_exp_f32_e32 v49, v49
	v_exp_f32_e32 v50, v50
	v_exp_f32_e32 v51, v51
	v_add_f32_e32 v84, v50, v66
	v_add_f32_e32 v85, v51, v67
	v_add_f32_e32 v86, v48, v64
	v_add_f32_e32 v87, v49, v65
	v_cvt_pk_bf16_f32 v64, v64, v65
	v_cvt_pk_bf16_f32 v65, v66, v67
	v_cvt_pk_bf16_f32 v48, v48, v49
	v_cvt_pk_bf16_f32 v49, v50, v51
	s_waitcnt lgkmcnt(7)
	v_mfma_f32_32x32x16_bf16 v[96:111], v[80:83], v[118:121], v[32:47]
	v_exp_f32_e32 v50, v68
	v_exp_f32_e32 v51, v69
	v_exp_f32_e32 v68, v70
	v_exp_f32_e32 v69, v71
	v_add_f32_e32 v70, v50, v86
	v_add_f32_e32 v71, v51, v87
	v_add_f32_e32 v181, v68, v84
	v_add_f32_e32 v228, v69, v85
	v_cvt_pk_bf16_f32 v66, v50, v51
	v_cvt_pk_bf16_f32 v67, v68, v69
	s_waitcnt lgkmcnt(6)
	v_mfma_f32_32x32x16_bf16 v[80:95], v[182:185], v[118:121], v[32:47]
	v_exp_f32_e32 v50, v52
	v_exp_f32_e32 v51, v53
	v_exp_f32_e32 v52, v54
	v_exp_f32_e32 v53, v55
	v_add_f32_e32 v54, v50, v70
	v_add_f32_e32 v55, v51, v71
	v_add_f32_e32 v68, v52, v181
	v_add_f32_e32 v69, v53, v228
	v_cvt_pk_bf16_f32 v50, v50, v51
	v_cvt_pk_bf16_f32 v51, v52, v53
	s_waitcnt lgkmcnt(5)
	v_mfma_f32_32x32x16_bf16 v[96:111], v[186:189], v[122:125], v[96:111]
	v_exp_f32_e32 v52, v72
	v_exp_f32_e32 v53, v73
	v_exp_f32_e32 v70, v74
	v_exp_f32_e32 v71, v75
	v_add_f32_e32 v54, v52, v54
	v_add_f32_e32 v55, v53, v55
	v_add_f32_e32 v72, v70, v68
	v_add_f32_e32 v73, v71, v69
	v_cvt_pk_bf16_f32 v68, v52, v53
	v_cvt_pk_bf16_f32 v69, v70, v71
	s_waitcnt lgkmcnt(4)
	v_mfma_f32_32x32x16_bf16 v[80:95], v[190:193], v[122:125], v[80:95]
	v_exp_f32_e32 v52, v56
	v_exp_f32_e32 v53, v57
	v_exp_f32_e32 v57, v58
	v_exp_f32_e32 v58, v59
	v_add_f32_e32 v54, v52, v54
	v_add_f32_e32 v55, v53, v55
	v_add_f32_e32 v59, v57, v72
	v_add_f32_e32 v70, v58, v73
	v_cvt_pk_bf16_f32 v56, v52, v53
	v_cvt_pk_bf16_f32 v57, v57, v58
	s_waitcnt lgkmcnt(3)
	v_mfma_f32_32x32x16_bf16 v[96:111], v[200:203], v[126:129], v[96:111]
	v_exp_f32_e32 v52, v76
	v_exp_f32_e32 v53, v77
	v_exp_f32_e32 v58, v78
	v_exp_f32_e32 v71, v79
	v_add_f32_e32 v54, v52, v54
	v_add_f32_e32 v55, v53, v55
	v_add_f32_e32 v59, v58, v59
	v_add_f32_e32 v72, v71, v70
	v_cvt_pk_bf16_f32 v70, v52, v53
	v_cvt_pk_bf16_f32 v71, v58, v71
	s_waitcnt lgkmcnt(2)
	v_mfma_f32_32x32x16_bf16 v[80:95], v[204:207], v[126:129], v[80:95]
	v_exp_f32_e32 v58, v60
	v_exp_f32_e32 v60, v61
	v_exp_f32_e32 v61, v62
	v_exp_f32_e32 v62, v63
	v_add_f32_e32 v52, v58, v54
	v_add_f32_e32 v53, v60, v55
	v_add_f32_e32 v54, v61, v59
	v_add_f32_e32 v55, v62, v72
	v_cvt_pk_bf16_f32 v58, v58, v60
	v_cvt_pk_bf16_f32 v59, v61, v62
	s_waitcnt lgkmcnt(1)
	v_mfma_f32_32x32x16_bf16 v[96:111], v[208:211], v[130:133], v[96:111]
	s_waitcnt lgkmcnt(0)
	v_mfma_f32_32x32x16_bf16 v[80:95], v[212:215], v[130:133], v[80:95]
	v_add_f32_e32 v182, v52, v53
	v_add_f32_e32 v183, v54, v55
	v_add_f32_e32 v182, v182, v183
	v_add_f32_e32 v169, v169, v182
	s_waitcnt vmcnt(2)
	s_waitcnt lgkmcnt(0)
	s_barrier
	s_add_i32 m0, s40, 49152
	s_nop 0
	global_load_lds_dwordx4 v174, s[84:85]
	s_add_i32 m0, s41, 8192
	s_nop 0
	global_load_lds_dwordx4 v172, s[82:83]
	s_add_u32 s84, s84, 0x48000
	s_addc_u32 s85, s85, 0
	s_add_u32 s82, s82, 0x48000
	s_addc_u32 s83, s83, 0
	ds_read_b64_tr_b16 v[60:61], v180 offset:32768
	ds_read_b64_tr_b16 v[62:63], v180 offset:33280
	ds_read_b64_tr_b16 v[72:73], v180 offset:36864
	ds_read_b64_tr_b16 v[74:75], v180 offset:37376
	s_waitcnt lgkmcnt(2)
	v_mfma_f32_32x32x16_bf16 v[16:31], v[60:63], v[64:67], v[16:31]
	s_waitcnt lgkmcnt(0)
	v_mfma_f32_32x32x16_bf16 v[0:15], v[72:75], v[64:67], v[0:15]
	ds_read_b64_tr_b16 v[60:61], v180 offset:33792
	ds_read_b64_tr_b16 v[62:63], v180 offset:34304
	ds_read_b64_tr_b16 v[64:65], v180 offset:37888
	ds_read_b64_tr_b16 v[66:67], v180 offset:38400
	s_waitcnt lgkmcnt(2)
	v_mfma_f32_32x32x16_bf16 v[16:31], v[60:63], v[68:71], v[16:31]
	s_waitcnt lgkmcnt(0)
	v_mfma_f32_32x32x16_bf16 v[0:15], v[64:67], v[68:71], v[0:15]
	ds_read_b64_tr_b16 v[60:61], v180 offset:34816
	ds_read_b64_tr_b16 v[62:63], v180 offset:35328
	ds_read_b64_tr_b16 v[64:65], v180 offset:38912
	ds_read_b64_tr_b16 v[66:67], v180 offset:39424
	s_waitcnt lgkmcnt(2)
	v_mfma_f32_32x32x16_bf16 v[16:31], v[60:63], v[48:51], v[16:31]
	s_waitcnt lgkmcnt(0)
	v_mfma_f32_32x32x16_bf16 v[0:15], v[64:67], v[48:51], v[0:15]
	ds_read_b64_tr_b16 v[48:49], v180 offset:35840
	ds_read_b64_tr_b16 v[50:51], v180 offset:36352
	ds_read_b64_tr_b16 v[60:61], v180 offset:39936
	ds_read_b64_tr_b16 v[62:63], v180 offset:40448
	s_waitcnt lgkmcnt(2)
	v_mfma_f32_32x32x16_bf16 v[16:31], v[48:51], v[56:59], v[16:31]
	s_waitcnt lgkmcnt(0)
	v_mfma_f32_32x32x16_bf16 v[0:15], v[60:63], v[56:59], v[0:15]
	ds_read_b128 v[182:185], v179
	ds_read_b128 v[186:189], v179 offset:512
	ds_read_b128 v[190:193], v179 offset:2048
	ds_read_b128 v[200:203], v179 offset:2560
	ds_read_b128 v[204:207], v179 offset:4096
	ds_read_b128 v[208:211], v179 offset:4608
	ds_read_b128 v[212:215], v179 offset:6144
	ds_read_b128 v[146:149], v179 offset:6656
	v_exp_f32_e32 v64, v96
	v_exp_f32_e32 v65, v97
	v_exp_f32_e32 v66, v98
	v_exp_f32_e32 v67, v99
	v_cvt_pk_bf16_f32 v96, v64, v65
	v_cvt_pk_bf16_f32 v97, v66, v67
	v_exp_f32_e32 v68, v80
	v_exp_f32_e32 v69, v81
	v_exp_f32_e32 v70, v82
	v_exp_f32_e32 v71, v83
	v_cvt_pk_bf16_f32 v80, v68, v69
	v_cvt_pk_bf16_f32 v81, v70, v71
	v_add_f32_e32 v68, v68, v64
	v_add_f32_e32 v69, v69, v65
	v_add_f32_e32 v82, v70, v66
	v_add_f32_e32 v83, v71, v67
	v_exp_f32_e32 v98, v100
	v_exp_f32_e32 v99, v101
	v_exp_f32_e32 v100, v102
	v_exp_f32_e32 v101, v103
	v_add_f32_e32 v102, v98, v68
	v_add_f32_e32 v103, v99, v69
	s_waitcnt lgkmcnt(7)
	v_mfma_f32_32x32x16_bf16 v[64:79], v[182:185], v[118:121], v[32:47]
	v_add_f32_e32 v82, v100, v82
	v_add_f32_e32 v83, v101, v83
	v_cvt_pk_bf16_f32 v98, v98, v99
	v_cvt_pk_bf16_f32 v99, v100, v101
	s_waitcnt lgkmcnt(6)
	v_mfma_f32_32x32x16_bf16 v[48:63], v[186:189], v[118:121], v[32:47]
	v_exp_f32_e32 v84, v84
	v_exp_f32_e32 v85, v85
	v_exp_f32_e32 v86, v86
	v_exp_f32_e32 v87, v87
	v_add_f32_e32 v100, v84, v102
	v_add_f32_e32 v101, v85, v103
	v_add_f32_e32 v102, v86, v82
	v_add_f32_e32 v103, v87, v83
	v_cvt_pk_bf16_f32 v82, v84, v85
	v_cvt_pk_bf16_f32 v83, v86, v87
	s_waitcnt lgkmcnt(5)
	v_mfma_f32_32x32x16_bf16 v[64:79], v[190:193], v[122:125], v[64:79]
	v_exp_f32_e32 v84, v104
	v_exp_f32_e32 v85, v105
	v_exp_f32_e32 v86, v106
	v_exp_f32_e32 v87, v107
	v_add_f32_e32 v104, v84, v100
	v_add_f32_e32 v105, v85, v101
	v_add_f32_e32 v102, v86, v102
	v_add_f32_e32 v103, v87, v103
	v_cvt_pk_bf16_f32 v100, v84, v85
	v_cvt_pk_bf16_f32 v101, v86, v87
	s_waitcnt lgkmcnt(4)
	v_mfma_f32_32x32x16_bf16 v[48:63], v[200:203], v[122:125], v[48:63]
	v_exp_f32_e32 v84, v88
	v_exp_f32_e32 v85, v89
	v_exp_f32_e32 v86, v90
	v_exp_f32_e32 v87, v91
	v_add_f32_e32 v90, v84, v104
	v_add_f32_e32 v91, v85, v105
	v_add_f32_e32 v102, v86, v102
	v_add_f32_e32 v103, v87, v103
	v_cvt_pk_bf16_f32 v88, v84, v85
	v_cvt_pk_bf16_f32 v89, v86, v87
	s_waitcnt lgkmcnt(3)
	v_mfma_f32_32x32x16_bf16 v[64:79], v[204:207], v[126:129], v[64:79]
	v_exp_f32_e32 v84, v108
	v_exp_f32_e32 v85, v109
	v_exp_f32_e32 v86, v110
	v_exp_f32_e32 v87, v111
	v_add_f32_e32 v90, v84, v90
	v_add_f32_e32 v91, v85, v91
	v_add_f32_e32 v104, v86, v102
	v_add_f32_e32 v105, v87, v103
	v_cvt_pk_bf16_f32 v102, v84, v85
	v_cvt_pk_bf16_f32 v103, v86, v87
	s_waitcnt lgkmcnt(2)
	v_mfma_f32_32x32x16_bf16 v[48:63], v[208:211], v[126:129], v[48:63]
	v_exp_f32_e32 v92, v92
	v_exp_f32_e32 v93, v93
	v_exp_f32_e32 v94, v94
	v_exp_f32_e32 v95, v95
	v_add_f32_e32 v84, v92, v90
	v_add_f32_e32 v85, v93, v91
	v_add_f32_e32 v86, v94, v104
	v_add_f32_e32 v87, v95, v105
	v_cvt_pk_bf16_f32 v90, v92, v93
	v_cvt_pk_bf16_f32 v91, v94, v95
	s_waitcnt lgkmcnt(1)
	v_mfma_f32_32x32x16_bf16 v[64:79], v[212:215], v[130:133], v[64:79]
	s_waitcnt lgkmcnt(0)
	v_mfma_f32_32x32x16_bf16 v[48:63], v[146:149], v[130:133], v[48:63]
	v_add_f32_e32 v182, v84, v85
	v_add_f32_e32 v183, v86, v87
	v_add_f32_e32 v182, v182, v183
	v_add_f32_e32 v169, v169, v182
	s_waitcnt vmcnt(2)
	s_waitcnt lgkmcnt(0)
	s_barrier
	s_mov_b32 s80, 4
; __device__ __forceinline__ void attn_unit(LAS unsigned char* lds, bf16_t* P, const float* qgain, const float* rope, int s, int h, int qb, int lane, int wid, bool dry) {
;     ...
;     for (int t = 0; t < NT; t += 2) {
;         ASTEP(t, pA0, pA1, pB0, pB1, krA, vrA, krB, vrB);
;         ASTEP(t + 1, pB0, pB1, pA0, pA1, krB, vrB, krA, vrA);
;     }
.Lfa_g1_loop:
	s_add_i32 m0, s40, 57344
	s_nop 0
	global_load_lds_dwordx4 v174, s[84:85]
	s_add_i32 m0, s41, 16384
	s_nop 0
	global_load_lds_dwordx4 v172, s[82:83]
	s_add_u32 s84, s84, 0x48000
	s_addc_u32 s85, s85, 0
	s_add_u32 s82, s82, 0x48000
	s_addc_u32 s83, s83, 0
	ds_read_b64_tr_b16 v[92:93], v180 offset:40960
	ds_read_b64_tr_b16 v[94:95], v180 offset:41472
	ds_read_b64_tr_b16 v[104:105], v180 offset:45056
	ds_read_b64_tr_b16 v[106:107], v180 offset:45568
	s_waitcnt lgkmcnt(2)
	v_mfma_f32_32x32x16_bf16 v[16:31], v[92:95], v[96:99], v[16:31]
	s_waitcnt lgkmcnt(0)
	v_mfma_f32_32x32x16_bf16 v[0:15], v[104:107], v[96:99], v[0:15]
	ds_read_b64_tr_b16 v[92:93], v180 offset:41984
	ds_read_b64_tr_b16 v[94:95], v180 offset:42496
	ds_read_b64_tr_b16 v[96:97], v180 offset:46080
	ds_read_b64_tr_b16 v[98:99], v180 offset:46592
	s_waitcnt lgkmcnt(2)
	v_mfma_f32_32x32x16_bf16 v[16:31], v[92:95], v[100:103], v[16:31]
	s_waitcnt lgkmcnt(0)
	v_mfma_f32_32x32x16_bf16 v[0:15], v[96:99], v[100:103], v[0:15]
	ds_read_b64_tr_b16 v[92:93], v180 offset:43008
	ds_read_b64_tr_b16 v[94:95], v180 offset:43520
	ds_read_b64_tr_b16 v[96:97], v180 offset:47104
	ds_read_b64_tr_b16 v[98:99], v180 offset:47616
	s_waitcnt lgkmcnt(2)
	v_mfma_f32_32x32x16_bf16 v[16:31], v[92:95], v[80:83], v[16:31]
	s_waitcnt lgkmcnt(0)
	v_mfma_f32_32x32x16_bf16 v[0:15], v[96:99], v[80:83], v[0:15]
	ds_read_b64_tr_b16 v[80:81], v180 offset:44032
	ds_read_b64_tr_b16 v[82:83], v180 offset:44544
	ds_read_b64_tr_b16 v[92:93], v180 offset:48128
	ds_read_b64_tr_b16 v[94:95], v180 offset:48640
	s_waitcnt lgkmcnt(2)
	v_mfma_f32_32x32x16_bf16 v[16:31], v[80:83], v[88:91], v[16:31]
	s_waitcnt lgkmcnt(0)
	v_mfma_f32_32x32x16_bf16 v[0:15], v[92:95], v[88:91], v[0:15]
	ds_read_b128 v[80:83], v179 offset:8192
	ds_read_b128 v[182:185], v179 offset:8704
	ds_read_b128 v[186:189], v179 offset:10240
	ds_read_b128 v[190:193], v179 offset:10752
	ds_read_b128 v[200:203], v179 offset:12288
	ds_read_b128 v[204:207], v179 offset:12800
	ds_read_b128 v[208:211], v179 offset:14336
	ds_read_b128 v[212:215], v179 offset:14848
	v_exp_f32_e32 v64, v64
	v_exp_f32_e32 v65, v65
	v_exp_f32_e32 v66, v66
	v_exp_f32_e32 v67, v67
	v_exp_f32_e32 v48, v48
	v_exp_f32_e32 v49, v49
	v_exp_f32_e32 v50, v50
	v_exp_f32_e32 v51, v51
	v_add_f32_e32 v84, v50, v66
	v_add_f32_e32 v85, v51, v67
	v_add_f32_e32 v86, v48, v64
	v_add_f32_e32 v87, v49, v65
	v_cvt_pk_bf16_f32 v64, v64, v65
	v_cvt_pk_bf16_f32 v65, v66, v67
	v_cvt_pk_bf16_f32 v48, v48, v49
	v_cvt_pk_bf16_f32 v49, v50, v51
	s_waitcnt lgkmcnt(7)
	v_mfma_f32_32x32x16_bf16 v[96:111], v[80:83], v[118:121], v[32:47]
	v_exp_f32_e32 v50, v68
	v_exp_f32_e32 v51, v69
	v_exp_f32_e32 v68, v70
	v_exp_f32_e32 v69, v71
	v_add_f32_e32 v70, v50, v86
	v_add_f32_e32 v71, v51, v87
	v_add_f32_e32 v181, v68, v84
	v_add_f32_e32 v228, v69, v85
	v_cvt_pk_bf16_f32 v66, v50, v51
	v_cvt_pk_bf16_f32 v67, v68, v69
	s_waitcnt lgkmcnt(6)
	v_mfma_f32_32x32x16_bf16 v[80:95], v[182:185], v[118:121], v[32:47]
	v_exp_f32_e32 v50, v52
	v_exp_f32_e32 v51, v53
	v_exp_f32_e32 v52, v54
	v_exp_f32_e32 v53, v55
	v_add_f32_e32 v54, v50, v70
	v_add_f32_e32 v55, v51, v71
	v_add_f32_e32 v68, v52, v181
	v_add_f32_e32 v69, v53, v228
	v_cvt_pk_bf16_f32 v50, v50, v51
	v_cvt_pk_bf16_f32 v51, v52, v53
	s_waitcnt lgkmcnt(5)
	v_mfma_f32_32x32x16_bf16 v[96:111], v[186:189], v[122:125], v[96:111]
	v_exp_f32_e32 v52, v72
	v_exp_f32_e32 v53, v73
	v_exp_f32_e32 v70, v74
	v_exp_f32_e32 v71, v75
	v_add_f32_e32 v54, v52, v54
	v_add_f32_e32 v55, v53, v55
	v_add_f32_e32 v72, v70, v68
	v_add_f32_e32 v73, v71, v69
	v_cvt_pk_bf16_f32 v68, v52, v53
	v_cvt_pk_bf16_f32 v69, v70, v71
	s_waitcnt lgkmcnt(4)
	v_mfma_f32_32x32x16_bf16 v[80:95], v[190:193], v[122:125], v[80:95]
	v_exp_f32_e32 v52, v56
	v_exp_f32_e32 v53, v57
	v_exp_f32_e32 v57, v58
	v_exp_f32_e32 v58, v59
	v_add_f32_e32 v54, v52, v54
	v_add_f32_e32 v55, v53, v55
	v_add_f32_e32 v59, v57, v72
	v_add_f32_e32 v70, v58, v73
	v_cvt_pk_bf16_f32 v56, v52, v53
	v_cvt_pk_bf16_f32 v57, v57, v58
	s_waitcnt lgkmcnt(3)
	v_mfma_f32_32x32x16_bf16 v[96:111], v[200:203], v[126:129], v[96:111]
	v_exp_f32_e32 v52, v76
	v_exp_f32_e32 v53, v77
	v_exp_f32_e32 v58, v78
	v_exp_f32_e32 v71, v79
	v_add_f32_e32 v54, v52, v54
	v_add_f32_e32 v55, v53, v55
	v_add_f32_e32 v59, v58, v59
	v_add_f32_e32 v72, v71, v70
	v_cvt_pk_bf16_f32 v70, v52, v53
	v_cvt_pk_bf16_f32 v71, v58, v71
	s_waitcnt lgkmcnt(2)
	v_mfma_f32_32x32x16_bf16 v[80:95], v[204:207], v[126:129], v[80:95]
	v_exp_f32_e32 v58, v60
	v_exp_f32_e32 v60, v61
	v_exp_f32_e32 v61, v62
	v_exp_f32_e32 v62, v63
	v_add_f32_e32 v52, v58, v54
	v_add_f32_e32 v53, v60, v55
	v_add_f32_e32 v54, v61, v59
	v_add_f32_e32 v55, v62, v72
	v_cvt_pk_bf16_f32 v58, v58, v60
	v_cvt_pk_bf16_f32 v59, v61, v62
	s_waitcnt lgkmcnt(1)
	v_mfma_f32_32x32x16_bf16 v[96:111], v[208:211], v[130:133], v[96:111]
	s_waitcnt lgkmcnt(0)
	v_mfma_f32_32x32x16_bf16 v[80:95], v[212:215], v[130:133], v[80:95]
	v_add_f32_e32 v182, v52, v53
	v_add_f32_e32 v183, v54, v55
	v_add_f32_e32 v182, v182, v183
	v_add_f32_e32 v169, v169, v182
	s_waitcnt vmcnt(2)
	s_waitcnt lgkmcnt(0)
	s_barrier
	s_add_i32 m0, s40, 0
	s_nop 0
	global_load_lds_dwordx4 v174, s[84:85]
	s_add_i32 m0, s41, 24576
	s_nop 0
	global_load_lds_dwordx4 v172, s[82:83]
	s_add_u32 s84, s84, 0x48000
	s_addc_u32 s85, s85, 0
	s_add_u32 s82, s82, 0x48000
	s_addc_u32 s83, s83, 0
	ds_read_b64_tr_b16 v[60:61], v180 offset:16384
	ds_read_b64_tr_b16 v[62:63], v180 offset:16896
	ds_read_b64_tr_b16 v[72:73], v180 offset:20480
	ds_read_b64_tr_b16 v[74:75], v180 offset:20992
	s_waitcnt lgkmcnt(2)
	v_mfma_f32_32x32x16_bf16 v[16:31], v[60:63], v[64:67], v[16:31]
	s_waitcnt lgkmcnt(0)
	v_mfma_f32_32x32x16_bf16 v[0:15], v[72:75], v[64:67], v[0:15]
	ds_read_b64_tr_b16 v[60:61], v180 offset:17408
	ds_read_b64_tr_b16 v[62:63], v180 offset:17920
	ds_read_b64_tr_b16 v[64:65], v180 offset:21504
	ds_read_b64_tr_b16 v[66:67], v180 offset:22016
	s_waitcnt lgkmcnt(2)
	v_mfma_f32_32x32x16_bf16 v[16:31], v[60:63], v[68:71], v[16:31]
	s_waitcnt lgkmcnt(0)
	v_mfma_f32_32x32x16_bf16 v[0:15], v[64:67], v[68:71], v[0:15]
	ds_read_b64_tr_b16 v[60:61], v180 offset:18432
	ds_read_b64_tr_b16 v[62:63], v180 offset:18944
	ds_read_b64_tr_b16 v[64:65], v180 offset:22528
	ds_read_b64_tr_b16 v[66:67], v180 offset:23040
	s_waitcnt lgkmcnt(2)
	v_mfma_f32_32x32x16_bf16 v[16:31], v[60:63], v[48:51], v[16:31]
	s_waitcnt lgkmcnt(0)
	v_mfma_f32_32x32x16_bf16 v[0:15], v[64:67], v[48:51], v[0:15]
	ds_read_b64_tr_b16 v[48:49], v180 offset:19456
	ds_read_b64_tr_b16 v[50:51], v180 offset:19968
	ds_read_b64_tr_b16 v[60:61], v180 offset:23552
	ds_read_b64_tr_b16 v[62:63], v180 offset:24064
	s_waitcnt lgkmcnt(2)
	v_mfma_f32_32x32x16_bf16 v[16:31], v[48:51], v[56:59], v[16:31]
	s_waitcnt lgkmcnt(0)
	v_mfma_f32_32x32x16_bf16 v[0:15], v[60:63], v[56:59], v[0:15]
	ds_read_b128 v[182:185], v179 offset:49152
	ds_read_b128 v[186:189], v179 offset:49664
	ds_read_b128 v[190:193], v179 offset:51200
	ds_read_b128 v[200:203], v179 offset:51712
	ds_read_b128 v[204:207], v179 offset:53248
	ds_read_b128 v[208:211], v179 offset:53760
	ds_read_b128 v[212:215], v179 offset:55296
	ds_read_b128 v[146:149], v179 offset:55808
	v_exp_f32_e32 v64, v96
	v_exp_f32_e32 v65, v97
	v_exp_f32_e32 v66, v98
	v_exp_f32_e32 v67, v99
	v_cvt_pk_bf16_f32 v96, v64, v65
	v_cvt_pk_bf16_f32 v97, v66, v67
	v_exp_f32_e32 v68, v80
	v_exp_f32_e32 v69, v81
	v_exp_f32_e32 v70, v82
	v_exp_f32_e32 v71, v83
	v_cvt_pk_bf16_f32 v80, v68, v69
	v_cvt_pk_bf16_f32 v81, v70, v71
	v_add_f32_e32 v68, v68, v64
	v_add_f32_e32 v69, v69, v65
	v_add_f32_e32 v82, v70, v66
	v_add_f32_e32 v83, v71, v67
	v_exp_f32_e32 v98, v100
	v_exp_f32_e32 v99, v101
	v_exp_f32_e32 v100, v102
	v_exp_f32_e32 v101, v103
	v_add_f32_e32 v102, v98, v68
	v_add_f32_e32 v103, v99, v69
	s_waitcnt lgkmcnt(7)
	v_mfma_f32_32x32x16_bf16 v[64:79], v[182:185], v[118:121], v[32:47]
	v_add_f32_e32 v82, v100, v82
	v_add_f32_e32 v83, v101, v83
	v_cvt_pk_bf16_f32 v98, v98, v99
	v_cvt_pk_bf16_f32 v99, v100, v101
	s_waitcnt lgkmcnt(6)
	v_mfma_f32_32x32x16_bf16 v[48:63], v[186:189], v[118:121], v[32:47]
	v_exp_f32_e32 v84, v84
	v_exp_f32_e32 v85, v85
	v_exp_f32_e32 v86, v86
	v_exp_f32_e32 v87, v87
	v_add_f32_e32 v100, v84, v102
	v_add_f32_e32 v101, v85, v103
	v_add_f32_e32 v102, v86, v82
	v_add_f32_e32 v103, v87, v83
	v_cvt_pk_bf16_f32 v82, v84, v85
	v_cvt_pk_bf16_f32 v83, v86, v87
	s_waitcnt lgkmcnt(5)
	v_mfma_f32_32x32x16_bf16 v[64:79], v[190:193], v[122:125], v[64:79]
	v_exp_f32_e32 v84, v104
	v_exp_f32_e32 v85, v105
	v_exp_f32_e32 v86, v106
	v_exp_f32_e32 v87, v107
	v_add_f32_e32 v104, v84, v100
	v_add_f32_e32 v105, v85, v101
	v_add_f32_e32 v102, v86, v102
	v_add_f32_e32 v103, v87, v103
	v_cvt_pk_bf16_f32 v100, v84, v85
	v_cvt_pk_bf16_f32 v101, v86, v87
	s_waitcnt lgkmcnt(4)
	v_mfma_f32_32x32x16_bf16 v[48:63], v[200:203], v[122:125], v[48:63]
	v_exp_f32_e32 v84, v88
	v_exp_f32_e32 v85, v89
	v_exp_f32_e32 v86, v90
	v_exp_f32_e32 v87, v91
	v_add_f32_e32 v90, v84, v104
	v_add_f32_e32 v91, v85, v105
	v_add_f32_e32 v102, v86, v102
	v_add_f32_e32 v103, v87, v103
	v_cvt_pk_bf16_f32 v88, v84, v85
	v_cvt_pk_bf16_f32 v89, v86, v87
	s_waitcnt lgkmcnt(3)
	v_mfma_f32_32x32x16_bf16 v[64:79], v[204:207], v[126:129], v[64:79]
	v_exp_f32_e32 v84, v108
	v_exp_f32_e32 v85, v109
	v_exp_f32_e32 v86, v110
	v_exp_f32_e32 v87, v111
	v_add_f32_e32 v90, v84, v90
	v_add_f32_e32 v91, v85, v91
	v_add_f32_e32 v104, v86, v102
	v_add_f32_e32 v105, v87, v103
	v_cvt_pk_bf16_f32 v102, v84, v85
	v_cvt_pk_bf16_f32 v103, v86, v87
	s_waitcnt lgkmcnt(2)
	v_mfma_f32_32x32x16_bf16 v[48:63], v[208:211], v[126:129], v[48:63]
	v_exp_f32_e32 v92, v92
	v_exp_f32_e32 v93, v93
	v_exp_f32_e32 v94, v94
	v_exp_f32_e32 v95, v95
	v_add_f32_e32 v84, v92, v90
	v_add_f32_e32 v85, v93, v91
	v_add_f32_e32 v86, v94, v104
	v_add_f32_e32 v87, v95, v105
	v_cvt_pk_bf16_f32 v90, v92, v93
	v_cvt_pk_bf16_f32 v91, v94, v95
	s_waitcnt lgkmcnt(1)
	v_mfma_f32_32x32x16_bf16 v[64:79], v[212:215], v[130:133], v[64:79]
	s_waitcnt lgkmcnt(0)
	v_mfma_f32_32x32x16_bf16 v[48:63], v[146:149], v[130:133], v[48:63]
	v_add_f32_e32 v182, v84, v85
	v_add_f32_e32 v183, v86, v87
	v_add_f32_e32 v182, v182, v183
	v_add_f32_e32 v169, v169, v182
	s_waitcnt vmcnt(2)
	s_waitcnt lgkmcnt(0)
	s_barrier
	s_add_i32 m0, s40, 8192
	s_nop 0
	global_load_lds_dwordx4 v174, s[84:85]
	s_add_i32 m0, s41, 0
	s_nop 0
	global_load_lds_dwordx4 v172, s[82:83]
	s_add_u32 s84, s84, 0x48000
	s_addc_u32 s85, s85, 0
	s_add_u32 s82, s82, 0x48000
	s_addc_u32 s83, s83, 0
	ds_read_b64_tr_b16 v[92:93], v180 offset:24576
	ds_read_b64_tr_b16 v[94:95], v180 offset:25088
	ds_read_b64_tr_b16 v[104:105], v180 offset:28672
	ds_read_b64_tr_b16 v[106:107], v180 offset:29184
	s_waitcnt lgkmcnt(2)
	v_mfma_f32_32x32x16_bf16 v[16:31], v[92:95], v[96:99], v[16:31]
	s_waitcnt lgkmcnt(0)
	v_mfma_f32_32x32x16_bf16 v[0:15], v[104:107], v[96:99], v[0:15]
	ds_read_b64_tr_b16 v[92:93], v180 offset:25600
	ds_read_b64_tr_b16 v[94:95], v180 offset:26112
	ds_read_b64_tr_b16 v[96:97], v180 offset:29696
	ds_read_b64_tr_b16 v[98:99], v180 offset:30208
	s_waitcnt lgkmcnt(2)
	v_mfma_f32_32x32x16_bf16 v[16:31], v[92:95], v[100:103], v[16:31]
	s_waitcnt lgkmcnt(0)
	v_mfma_f32_32x32x16_bf16 v[0:15], v[96:99], v[100:103], v[0:15]
	ds_read_b64_tr_b16 v[92:93], v180 offset:26624
	ds_read_b64_tr_b16 v[94:95], v180 offset:27136
	ds_read_b64_tr_b16 v[96:97], v180 offset:30720
	ds_read_b64_tr_b16 v[98:99], v180 offset:31232
	s_waitcnt lgkmcnt(2)
	v_mfma_f32_32x32x16_bf16 v[16:31], v[92:95], v[80:83], v[16:31]
	s_waitcnt lgkmcnt(0)
	v_mfma_f32_32x32x16_bf16 v[0:15], v[96:99], v[80:83], v[0:15]
	ds_read_b64_tr_b16 v[80:81], v180 offset:27648
	ds_read_b64_tr_b16 v[82:83], v180 offset:28160
	ds_read_b64_tr_b16 v[92:93], v180 offset:31744
	ds_read_b64_tr_b16 v[94:95], v180 offset:32256
	s_waitcnt lgkmcnt(2)
	v_mfma_f32_32x32x16_bf16 v[16:31], v[80:83], v[88:91], v[16:31]
	s_waitcnt lgkmcnt(0)
	v_mfma_f32_32x32x16_bf16 v[0:15], v[92:95], v[88:91], v[0:15]
	ds_read_b128 v[80:83], v179 offset:57344
	ds_read_b128 v[182:185], v179 offset:57856
	ds_read_b128 v[186:189], v179 offset:59392
	ds_read_b128 v[190:193], v179 offset:59904
	ds_read_b128 v[200:203], v179 offset:61440
	ds_read_b128 v[204:207], v179 offset:61952
	ds_read_b128 v[208:211], v179 offset:63488
	ds_read_b128 v[212:215], v179 offset:64000
	v_exp_f32_e32 v64, v64
	v_exp_f32_e32 v65, v65
	v_exp_f32_e32 v66, v66
	v_exp_f32_e32 v67, v67
	v_exp_f32_e32 v48, v48
	v_exp_f32_e32 v49, v49
	v_exp_f32_e32 v50, v50
	v_exp_f32_e32 v51, v51
	v_add_f32_e32 v84, v50, v66
	v_add_f32_e32 v85, v51, v67
	v_add_f32_e32 v86, v48, v64
	v_add_f32_e32 v87, v49, v65
	v_cvt_pk_bf16_f32 v64, v64, v65
	v_cvt_pk_bf16_f32 v65, v66, v67
	v_cvt_pk_bf16_f32 v48, v48, v49
	v_cvt_pk_bf16_f32 v49, v50, v51
	s_waitcnt lgkmcnt(7)
	v_mfma_f32_32x32x16_bf16 v[96:111], v[80:83], v[118:121], v[32:47]
	v_exp_f32_e32 v50, v68
	v_exp_f32_e32 v51, v69
	v_exp_f32_e32 v68, v70
	v_exp_f32_e32 v69, v71
	v_add_f32_e32 v70, v50, v86
	v_add_f32_e32 v71, v51, v87
	v_add_f32_e32 v181, v68, v84
	v_add_f32_e32 v228, v69, v85
	v_cvt_pk_bf16_f32 v66, v50, v51
	v_cvt_pk_bf16_f32 v67, v68, v69
	s_waitcnt lgkmcnt(6)
	v_mfma_f32_32x32x16_bf16 v[80:95], v[182:185], v[118:121], v[32:47]
	v_exp_f32_e32 v50, v52
	v_exp_f32_e32 v51, v53
	v_exp_f32_e32 v52, v54
	v_exp_f32_e32 v53, v55
	v_add_f32_e32 v54, v50, v70
	v_add_f32_e32 v55, v51, v71
	v_add_f32_e32 v68, v52, v181
	v_add_f32_e32 v69, v53, v228
	v_cvt_pk_bf16_f32 v50, v50, v51
	v_cvt_pk_bf16_f32 v51, v52, v53
	s_waitcnt lgkmcnt(5)
	v_mfma_f32_32x32x16_bf16 v[96:111], v[186:189], v[122:125], v[96:111]
	v_exp_f32_e32 v52, v72
	v_exp_f32_e32 v53, v73
	v_exp_f32_e32 v70, v74
	v_exp_f32_e32 v71, v75
	v_add_f32_e32 v54, v52, v54
	v_add_f32_e32 v55, v53, v55
	v_add_f32_e32 v72, v70, v68
	v_add_f32_e32 v73, v71, v69
	v_cvt_pk_bf16_f32 v68, v52, v53
	v_cvt_pk_bf16_f32 v69, v70, v71
	s_waitcnt lgkmcnt(4)
	v_mfma_f32_32x32x16_bf16 v[80:95], v[190:193], v[122:125], v[80:95]
	v_exp_f32_e32 v52, v56
	v_exp_f32_e32 v53, v57
	v_exp_f32_e32 v57, v58
	v_exp_f32_e32 v58, v59
	v_add_f32_e32 v54, v52, v54
	v_add_f32_e32 v55, v53, v55
	v_add_f32_e32 v59, v57, v72
	v_add_f32_e32 v70, v58, v73
	v_cvt_pk_bf16_f32 v56, v52, v53
	v_cvt_pk_bf16_f32 v57, v57, v58
	s_waitcnt lgkmcnt(3)
	v_mfma_f32_32x32x16_bf16 v[96:111], v[200:203], v[126:129], v[96:111]
	v_exp_f32_e32 v52, v76
	v_exp_f32_e32 v53, v77
	v_exp_f32_e32 v58, v78
	v_exp_f32_e32 v71, v79
	v_add_f32_e32 v54, v52, v54
	v_add_f32_e32 v55, v53, v55
	v_add_f32_e32 v59, v58, v59
	v_add_f32_e32 v72, v71, v70
	v_cvt_pk_bf16_f32 v70, v52, v53
	v_cvt_pk_bf16_f32 v71, v58, v71
	s_waitcnt lgkmcnt(2)
	v_mfma_f32_32x32x16_bf16 v[80:95], v[204:207], v[126:129], v[80:95]
	v_exp_f32_e32 v58, v60
	v_exp_f32_e32 v60, v61
	v_exp_f32_e32 v61, v62
	v_exp_f32_e32 v62, v63
	v_add_f32_e32 v52, v58, v54
	v_add_f32_e32 v53, v60, v55
	v_add_f32_e32 v54, v61, v59
	v_add_f32_e32 v55, v62, v72
	v_cvt_pk_bf16_f32 v58, v58, v60
	v_cvt_pk_bf16_f32 v59, v61, v62
	s_waitcnt lgkmcnt(1)
	v_mfma_f32_32x32x16_bf16 v[96:111], v[208:211], v[130:133], v[96:111]
	s_waitcnt lgkmcnt(0)
	v_mfma_f32_32x32x16_bf16 v[80:95], v[212:215], v[130:133], v[80:95]
	v_add_f32_e32 v182, v52, v53
	v_add_f32_e32 v183, v54, v55
	v_add_f32_e32 v182, v182, v183
	v_add_f32_e32 v169, v169, v182
	s_waitcnt vmcnt(2)
	s_waitcnt lgkmcnt(0)
	s_barrier
; __device__ __forceinline__ void attn_unit(LAS unsigned char* lds, bf16_t* P, const float* qgain, const float* rope, int s, int h, int qb, int lane, int wid, bool dry) {
;     ...
;     for (int t = 0; t < NT; t += 2) {
;         ASTEP(t, pA0, pA1, pB0, pB1, krA, vrA, krB, vrB);
;         ASTEP(t + 1, pB0, pB1, pA0, pA1, krB, vrB, krA, vrA);
;     }
	s_add_i32 m0, s40, 49152
	s_nop 0
	global_load_lds_dwordx4 v174, s[84:85]
	s_add_i32 m0, s41, 8192
	s_nop 0
	global_load_lds_dwordx4 v172, s[82:83]
	s_add_u32 s84, s84, 0x48000
	s_addc_u32 s85, s85, 0
	s_add_u32 s82, s82, 0x48000
	s_addc_u32 s83, s83, 0
	ds_read_b64_tr_b16 v[60:61], v180 offset:32768
	ds_read_b64_tr_b16 v[62:63], v180 offset:33280
	ds_read_b64_tr_b16 v[72:73], v180 offset:36864
	ds_read_b64_tr_b16 v[74:75], v180 offset:37376
	s_waitcnt lgkmcnt(2)
	v_mfma_f32_32x32x16_bf16 v[16:31], v[60:63], v[64:67], v[16:31]
	s_waitcnt lgkmcnt(0)
	v_mfma_f32_32x32x16_bf16 v[0:15], v[72:75], v[64:67], v[0:15]
	ds_read_b64_tr_b16 v[60:61], v180 offset:33792
	ds_read_b64_tr_b16 v[62:63], v180 offset:34304
	ds_read_b64_tr_b16 v[64:65], v180 offset:37888
	ds_read_b64_tr_b16 v[66:67], v180 offset:38400
	s_waitcnt lgkmcnt(2)
	v_mfma_f32_32x32x16_bf16 v[16:31], v[60:63], v[68:71], v[16:31]
	s_waitcnt lgkmcnt(0)
	v_mfma_f32_32x32x16_bf16 v[0:15], v[64:67], v[68:71], v[0:15]
	ds_read_b64_tr_b16 v[60:61], v180 offset:34816
	ds_read_b64_tr_b16 v[62:63], v180 offset:35328
	ds_read_b64_tr_b16 v[64:65], v180 offset:38912
	ds_read_b64_tr_b16 v[66:67], v180 offset:39424
	s_waitcnt lgkmcnt(2)
	v_mfma_f32_32x32x16_bf16 v[16:31], v[60:63], v[48:51], v[16:31]
	s_waitcnt lgkmcnt(0)
	v_mfma_f32_32x32x16_bf16 v[0:15], v[64:67], v[48:51], v[0:15]
	ds_read_b64_tr_b16 v[48:49], v180 offset:35840
	ds_read_b64_tr_b16 v[50:51], v180 offset:36352
	ds_read_b64_tr_b16 v[60:61], v180 offset:39936
	ds_read_b64_tr_b16 v[62:63], v180 offset:40448
	s_waitcnt lgkmcnt(2)
	v_mfma_f32_32x32x16_bf16 v[16:31], v[48:51], v[56:59], v[16:31]
	s_waitcnt lgkmcnt(0)
	v_mfma_f32_32x32x16_bf16 v[0:15], v[60:63], v[56:59], v[0:15]
	ds_read_b128 v[182:185], v179
	ds_read_b128 v[186:189], v179 offset:512
	ds_read_b128 v[190:193], v179 offset:2048
	ds_read_b128 v[200:203], v179 offset:2560
	ds_read_b128 v[204:207], v179 offset:4096
	ds_read_b128 v[208:211], v179 offset:4608
	ds_read_b128 v[212:215], v179 offset:6144
	ds_read_b128 v[146:149], v179 offset:6656
	v_exp_f32_e32 v64, v96
	v_exp_f32_e32 v65, v97
	v_exp_f32_e32 v66, v98
	v_exp_f32_e32 v67, v99
	v_cvt_pk_bf16_f32 v96, v64, v65
	v_cvt_pk_bf16_f32 v97, v66, v67
	v_exp_f32_e32 v68, v80
	v_exp_f32_e32 v69, v81
	v_exp_f32_e32 v70, v82
	v_exp_f32_e32 v71, v83
	v_cvt_pk_bf16_f32 v80, v68, v69
	v_cvt_pk_bf16_f32 v81, v70, v71
	v_add_f32_e32 v68, v68, v64
	v_add_f32_e32 v69, v69, v65
	v_add_f32_e32 v82, v70, v66
	v_add_f32_e32 v83, v71, v67
	v_exp_f32_e32 v98, v100
	v_exp_f32_e32 v99, v101
	v_exp_f32_e32 v100, v102
	v_exp_f32_e32 v101, v103
	v_add_f32_e32 v102, v98, v68
	v_add_f32_e32 v103, v99, v69
	s_waitcnt lgkmcnt(7)
	v_mfma_f32_32x32x16_bf16 v[64:79], v[182:185], v[118:121], v[32:47]
	v_add_f32_e32 v82, v100, v82
	v_add_f32_e32 v83, v101, v83
	v_cvt_pk_bf16_f32 v98, v98, v99
	v_cvt_pk_bf16_f32 v99, v100, v101
	s_waitcnt lgkmcnt(6)
	v_mfma_f32_32x32x16_bf16 v[48:63], v[186:189], v[118:121], v[32:47]
	v_exp_f32_e32 v84, v84
	v_exp_f32_e32 v85, v85
	v_exp_f32_e32 v86, v86
	v_exp_f32_e32 v87, v87
	v_add_f32_e32 v100, v84, v102
	v_add_f32_e32 v101, v85, v103
	v_add_f32_e32 v102, v86, v82
	v_add_f32_e32 v103, v87, v83
	v_cvt_pk_bf16_f32 v82, v84, v85
	v_cvt_pk_bf16_f32 v83, v86, v87
	s_waitcnt lgkmcnt(5)
	v_mfma_f32_32x32x16_bf16 v[64:79], v[190:193], v[122:125], v[64:79]
	v_exp_f32_e32 v84, v104
	v_exp_f32_e32 v85, v105
	v_exp_f32_e32 v86, v106
	v_exp_f32_e32 v87, v107
	v_add_f32_e32 v104, v84, v100
	v_add_f32_e32 v105, v85, v101
	v_add_f32_e32 v102, v86, v102
	v_add_f32_e32 v103, v87, v103
	v_cvt_pk_bf16_f32 v100, v84, v85
	v_cvt_pk_bf16_f32 v101, v86, v87
	s_waitcnt lgkmcnt(4)
	v_mfma_f32_32x32x16_bf16 v[48:63], v[200:203], v[122:125], v[48:63]
	v_exp_f32_e32 v84, v88
	v_exp_f32_e32 v85, v89
	v_exp_f32_e32 v86, v90
	v_exp_f32_e32 v87, v91
	v_add_f32_e32 v90, v84, v104
	v_add_f32_e32 v91, v85, v105
	v_add_f32_e32 v102, v86, v102
	v_add_f32_e32 v103, v87, v103
	v_cvt_pk_bf16_f32 v88, v84, v85
	v_cvt_pk_bf16_f32 v89, v86, v87
	s_waitcnt lgkmcnt(3)
	v_mfma_f32_32x32x16_bf16 v[64:79], v[204:207], v[126:129], v[64:79]
	v_exp_f32_e32 v84, v108
	v_exp_f32_e32 v85, v109
	v_exp_f32_e32 v86, v110
	v_exp_f32_e32 v87, v111
	v_add_f32_e32 v90, v84, v90
	v_add_f32_e32 v91, v85, v91
	v_add_f32_e32 v104, v86, v102
	v_add_f32_e32 v105, v87, v103
	v_cvt_pk_bf16_f32 v102, v84, v85
	v_cvt_pk_bf16_f32 v103, v86, v87
	s_waitcnt lgkmcnt(2)
	v_mfma_f32_32x32x16_bf16 v[48:63], v[208:211], v[126:129], v[48:63]
	v_exp_f32_e32 v92, v92
	v_exp_f32_e32 v93, v93
	v_exp_f32_e32 v94, v94
	v_exp_f32_e32 v95, v95
	v_add_f32_e32 v84, v92, v90
	v_add_f32_e32 v85, v93, v91
	v_add_f32_e32 v86, v94, v104
	v_add_f32_e32 v87, v95, v105
	v_cvt_pk_bf16_f32 v90, v92, v93
	v_cvt_pk_bf16_f32 v91, v94, v95
	s_waitcnt lgkmcnt(1)
	v_mfma_f32_32x32x16_bf16 v[64:79], v[212:215], v[130:133], v[64:79]
	s_waitcnt lgkmcnt(0)
	v_mfma_f32_32x32x16_bf16 v[48:63], v[146:149], v[130:133], v[48:63]
	v_add_f32_e32 v182, v84, v85
	v_add_f32_e32 v183, v86, v87
	v_add_f32_e32 v182, v182, v183
	v_add_f32_e32 v169, v169, v182
	s_waitcnt vmcnt(2)
	s_waitcnt lgkmcnt(0)
	s_barrier
	s_add_i32 s80, s80, 4
	s_cmp_lt_u32 s80, 60
	s_cbranch_scc1 .Lfa_g1_loop
	s_add_i32 m0, s40, 57344
	s_nop 0
	global_load_lds_dwordx4 v174, s[84:85]
	s_add_i32 m0, s41, 16384
	s_nop 0
	global_load_lds_dwordx4 v172, s[82:83]
	s_add_u32 s84, s84, 0x48000
	s_addc_u32 s85, s85, 0
	s_add_u32 s82, s82, 0x48000
	s_addc_u32 s83, s83, 0
	ds_read_b64_tr_b16 v[92:93], v180 offset:40960
	ds_read_b64_tr_b16 v[94:95], v180 offset:41472
	ds_read_b64_tr_b16 v[104:105], v180 offset:45056
	ds_read_b64_tr_b16 v[106:107], v180 offset:45568
	s_waitcnt lgkmcnt(2)
	v_mfma_f32_32x32x16_bf16 v[16:31], v[92:95], v[96:99], v[16:31]
	s_waitcnt lgkmcnt(0)
	v_mfma_f32_32x32x16_bf16 v[0:15], v[104:107], v[96:99], v[0:15]
	ds_read_b64_tr_b16 v[92:93], v180 offset:41984
	ds_read_b64_tr_b16 v[94:95], v180 offset:42496
	ds_read_b64_tr_b16 v[96:97], v180 offset:46080
	ds_read_b64_tr_b16 v[98:99], v180 offset:46592
	s_waitcnt lgkmcnt(2)
	v_mfma_f32_32x32x16_bf16 v[16:31], v[92:95], v[100:103], v[16:31]
	s_waitcnt lgkmcnt(0)
	v_mfma_f32_32x32x16_bf16 v[0:15], v[96:99], v[100:103], v[0:15]
	ds_read_b64_tr_b16 v[92:93], v180 offset:43008
	ds_read_b64_tr_b16 v[94:95], v180 offset:43520
	ds_read_b64_tr_b16 v[96:97], v180 offset:47104
	ds_read_b64_tr_b16 v[98:99], v180 offset:47616
	s_waitcnt lgkmcnt(2)
	v_mfma_f32_32x32x16_bf16 v[16:31], v[92:95], v[80:83], v[16:31]
	s_waitcnt lgkmcnt(0)
	v_mfma_f32_32x32x16_bf16 v[0:15], v[96:99], v[80:83], v[0:15]
	ds_read_b64_tr_b16 v[80:81], v180 offset:44032
	ds_read_b64_tr_b16 v[82:83], v180 offset:44544
	ds_read_b64_tr_b16 v[92:93], v180 offset:48128
	ds_read_b64_tr_b16 v[94:95], v180 offset:48640
	s_waitcnt lgkmcnt(2)
	v_mfma_f32_32x32x16_bf16 v[16:31], v[80:83], v[88:91], v[16:31]
	s_waitcnt lgkmcnt(0)
	v_mfma_f32_32x32x16_bf16 v[0:15], v[92:95], v[88:91], v[0:15]
	ds_read_b128 v[80:83], v179 offset:8192
	ds_read_b128 v[182:185], v179 offset:8704
	ds_read_b128 v[186:189], v179 offset:10240
	ds_read_b128 v[190:193], v179 offset:10752
	ds_read_b128 v[200:203], v179 offset:12288
	ds_read_b128 v[204:207], v179 offset:12800
	ds_read_b128 v[208:211], v179 offset:14336
	ds_read_b128 v[212:215], v179 offset:14848
	v_exp_f32_e32 v64, v64
	v_exp_f32_e32 v65, v65
	v_exp_f32_e32 v66, v66
	v_exp_f32_e32 v67, v67
	v_exp_f32_e32 v48, v48
	v_exp_f32_e32 v49, v49
	v_exp_f32_e32 v50, v50
	v_exp_f32_e32 v51, v51
	v_add_f32_e32 v84, v50, v66
	v_add_f32_e32 v85, v51, v67
	v_add_f32_e32 v86, v48, v64
	v_add_f32_e32 v87, v49, v65
	v_cvt_pk_bf16_f32 v64, v64, v65
	v_cvt_pk_bf16_f32 v65, v66, v67
	v_cvt_pk_bf16_f32 v48, v48, v49
	v_cvt_pk_bf16_f32 v49, v50, v51
	s_waitcnt lgkmcnt(7)
	v_mfma_f32_32x32x16_bf16 v[96:111], v[80:83], v[118:121], v[32:47]
	v_exp_f32_e32 v50, v68
	v_exp_f32_e32 v51, v69
	v_exp_f32_e32 v68, v70
	v_exp_f32_e32 v69, v71
	v_add_f32_e32 v70, v50, v86
	v_add_f32_e32 v71, v51, v87
	v_add_f32_e32 v181, v68, v84
	v_add_f32_e32 v228, v69, v85
	v_cvt_pk_bf16_f32 v66, v50, v51
	v_cvt_pk_bf16_f32 v67, v68, v69
	s_waitcnt lgkmcnt(6)
	v_mfma_f32_32x32x16_bf16 v[80:95], v[182:185], v[118:121], v[32:47]
	v_exp_f32_e32 v50, v52
	v_exp_f32_e32 v51, v53
	v_exp_f32_e32 v52, v54
	v_exp_f32_e32 v53, v55
	v_add_f32_e32 v54, v50, v70
	v_add_f32_e32 v55, v51, v71
	v_add_f32_e32 v68, v52, v181
	v_add_f32_e32 v69, v53, v228
	v_cvt_pk_bf16_f32 v50, v50, v51
	v_cvt_pk_bf16_f32 v51, v52, v53
	s_waitcnt lgkmcnt(5)
	v_mfma_f32_32x32x16_bf16 v[96:111], v[186:189], v[122:125], v[96:111]
	v_exp_f32_e32 v52, v72
	v_exp_f32_e32 v53, v73
	v_exp_f32_e32 v70, v74
	v_exp_f32_e32 v71, v75
	v_add_f32_e32 v54, v52, v54
	v_add_f32_e32 v55, v53, v55
	v_add_f32_e32 v72, v70, v68
	v_add_f32_e32 v73, v71, v69
	v_cvt_pk_bf16_f32 v68, v52, v53
	v_cvt_pk_bf16_f32 v69, v70, v71
	s_waitcnt lgkmcnt(4)
	v_mfma_f32_32x32x16_bf16 v[80:95], v[190:193], v[122:125], v[80:95]
	v_exp_f32_e32 v52, v56
	v_exp_f32_e32 v53, v57
	v_exp_f32_e32 v57, v58
	v_exp_f32_e32 v58, v59
	v_add_f32_e32 v54, v52, v54
	v_add_f32_e32 v55, v53, v55
	v_add_f32_e32 v59, v57, v72
	v_add_f32_e32 v70, v58, v73
	v_cvt_pk_bf16_f32 v56, v52, v53
	v_cvt_pk_bf16_f32 v57, v57, v58
	s_waitcnt lgkmcnt(3)
	v_mfma_f32_32x32x16_bf16 v[96:111], v[200:203], v[126:129], v[96:111]
	v_exp_f32_e32 v52, v76
	v_exp_f32_e32 v53, v77
	v_exp_f32_e32 v58, v78
	v_exp_f32_e32 v71, v79
	v_add_f32_e32 v54, v52, v54
	v_add_f32_e32 v55, v53, v55
	v_add_f32_e32 v59, v58, v59
	v_add_f32_e32 v72, v71, v70
	v_cvt_pk_bf16_f32 v70, v52, v53
	v_cvt_pk_bf16_f32 v71, v58, v71
	s_waitcnt lgkmcnt(2)
	v_mfma_f32_32x32x16_bf16 v[80:95], v[204:207], v[126:129], v[80:95]
	v_exp_f32_e32 v58, v60
	v_exp_f32_e32 v60, v61
	v_exp_f32_e32 v61, v62
	v_exp_f32_e32 v62, v63
	v_add_f32_e32 v52, v58, v54
	v_add_f32_e32 v53, v60, v55
	v_add_f32_e32 v54, v61, v59
	v_add_f32_e32 v55, v62, v72
	v_cvt_pk_bf16_f32 v58, v58, v60
	v_cvt_pk_bf16_f32 v59, v61, v62
	s_waitcnt lgkmcnt(1)
	v_mfma_f32_32x32x16_bf16 v[96:111], v[208:211], v[130:133], v[96:111]
	s_waitcnt lgkmcnt(0)
	v_mfma_f32_32x32x16_bf16 v[80:95], v[212:215], v[130:133], v[80:95]
	v_add_f32_e32 v182, v52, v53
	v_add_f32_e32 v183, v54, v55
	v_add_f32_e32 v182, v182, v183
	v_add_f32_e32 v169, v169, v182
	s_waitcnt vmcnt(2)
	s_waitcnt lgkmcnt(0)
	s_barrier
	s_add_i32 m0, s41, 24576
	s_nop 0
	global_load_lds_dwordx4 v172, s[82:83]
	s_add_u32 s84, s84, 0x48000
	s_addc_u32 s85, s85, 0
	s_add_u32 s82, s82, 0x48000
	s_addc_u32 s83, s83, 0
	ds_read_b64_tr_b16 v[60:61], v180 offset:16384
	ds_read_b64_tr_b16 v[62:63], v180 offset:16896
	ds_read_b64_tr_b16 v[72:73], v180 offset:20480
	ds_read_b64_tr_b16 v[74:75], v180 offset:20992
	s_waitcnt lgkmcnt(2)
	v_mfma_f32_32x32x16_bf16 v[16:31], v[60:63], v[64:67], v[16:31]
	s_waitcnt lgkmcnt(0)
	v_mfma_f32_32x32x16_bf16 v[0:15], v[72:75], v[64:67], v[0:15]
	ds_read_b64_tr_b16 v[60:61], v180 offset:17408
	ds_read_b64_tr_b16 v[62:63], v180 offset:17920
	ds_read_b64_tr_b16 v[64:65], v180 offset:21504
	ds_read_b64_tr_b16 v[66:67], v180 offset:22016
	s_waitcnt lgkmcnt(2)
	v_mfma_f32_32x32x16_bf16 v[16:31], v[60:63], v[68:71], v[16:31]
	s_waitcnt lgkmcnt(0)
	v_mfma_f32_32x32x16_bf16 v[0:15], v[64:67], v[68:71], v[0:15]
	ds_read_b64_tr_b16 v[60:61], v180 offset:18432
	ds_read_b64_tr_b16 v[62:63], v180 offset:18944
	ds_read_b64_tr_b16 v[64:65], v180 offset:22528
	ds_read_b64_tr_b16 v[66:67], v180 offset:23040
	s_waitcnt lgkmcnt(2)
	v_mfma_f32_32x32x16_bf16 v[16:31], v[60:63], v[48:51], v[16:31]
	s_waitcnt lgkmcnt(0)
	v_mfma_f32_32x32x16_bf16 v[0:15], v[64:67], v[48:51], v[0:15]
	ds_read_b64_tr_b16 v[48:49], v180 offset:19456
	ds_read_b64_tr_b16 v[50:51], v180 offset:19968
	ds_read_b64_tr_b16 v[60:61], v180 offset:23552
	ds_read_b64_tr_b16 v[62:63], v180 offset:24064
	s_waitcnt lgkmcnt(2)
	v_mfma_f32_32x32x16_bf16 v[16:31], v[48:51], v[56:59], v[16:31]
	s_waitcnt lgkmcnt(0)
	v_mfma_f32_32x32x16_bf16 v[0:15], v[60:63], v[56:59], v[0:15]
	ds_read_b128 v[182:185], v179 offset:49152
	ds_read_b128 v[186:189], v179 offset:49664
	ds_read_b128 v[190:193], v179 offset:51200
	ds_read_b128 v[200:203], v179 offset:51712
	ds_read_b128 v[204:207], v179 offset:53248
	ds_read_b128 v[208:211], v179 offset:53760
	ds_read_b128 v[212:215], v179 offset:55296
	ds_read_b128 v[146:149], v179 offset:55808
	v_exp_f32_e32 v64, v96
	v_exp_f32_e32 v65, v97
	v_exp_f32_e32 v66, v98
	v_exp_f32_e32 v67, v99
	v_cvt_pk_bf16_f32 v96, v64, v65
	v_cvt_pk_bf16_f32 v97, v66, v67
	v_exp_f32_e32 v68, v80
	v_exp_f32_e32 v69, v81
	v_exp_f32_e32 v70, v82
	v_exp_f32_e32 v71, v83
	v_cvt_pk_bf16_f32 v80, v68, v69
	v_cvt_pk_bf16_f32 v81, v70, v71
	v_add_f32_e32 v68, v68, v64
	v_add_f32_e32 v69, v69, v65
	v_add_f32_e32 v82, v70, v66
	v_add_f32_e32 v83, v71, v67
	v_exp_f32_e32 v98, v100
	v_exp_f32_e32 v99, v101
	v_exp_f32_e32 v100, v102
	v_exp_f32_e32 v101, v103
	v_add_f32_e32 v102, v98, v68
	v_add_f32_e32 v103, v99, v69
	s_waitcnt lgkmcnt(7)
	v_mfma_f32_32x32x16_bf16 v[64:79], v[182:185], v[118:121], v[32:47]
	v_add_f32_e32 v82, v100, v82
	v_add_f32_e32 v83, v101, v83
	v_cvt_pk_bf16_f32 v98, v98, v99
	v_cvt_pk_bf16_f32 v99, v100, v101
	s_waitcnt lgkmcnt(6)
	v_mfma_f32_32x32x16_bf16 v[48:63], v[186:189], v[118:121], v[32:47]
	v_exp_f32_e32 v84, v84
	v_exp_f32_e32 v85, v85
	v_exp_f32_e32 v86, v86
	v_exp_f32_e32 v87, v87
	v_add_f32_e32 v100, v84, v102
	v_add_f32_e32 v101, v85, v103
	v_add_f32_e32 v102, v86, v82
	v_add_f32_e32 v103, v87, v83
	v_cvt_pk_bf16_f32 v82, v84, v85
	v_cvt_pk_bf16_f32 v83, v86, v87
	s_waitcnt lgkmcnt(5)
	v_mfma_f32_32x32x16_bf16 v[64:79], v[190:193], v[122:125], v[64:79]
	v_exp_f32_e32 v84, v104
	v_exp_f32_e32 v85, v105
	v_exp_f32_e32 v86, v106
	v_exp_f32_e32 v87, v107
	v_add_f32_e32 v104, v84, v100
	v_add_f32_e32 v105, v85, v101
	v_add_f32_e32 v102, v86, v102
	v_add_f32_e32 v103, v87, v103
	v_cvt_pk_bf16_f32 v100, v84, v85
	v_cvt_pk_bf16_f32 v101, v86, v87
	s_waitcnt lgkmcnt(4)
	v_mfma_f32_32x32x16_bf16 v[48:63], v[200:203], v[122:125], v[48:63]
	v_exp_f32_e32 v84, v88
	v_exp_f32_e32 v85, v89
	v_exp_f32_e32 v86, v90
	v_exp_f32_e32 v87, v91
	v_add_f32_e32 v90, v84, v104
	v_add_f32_e32 v91, v85, v105
	v_add_f32_e32 v102, v86, v102
	v_add_f32_e32 v103, v87, v103
	v_cvt_pk_bf16_f32 v88, v84, v85
	v_cvt_pk_bf16_f32 v89, v86, v87
	s_waitcnt lgkmcnt(3)
	v_mfma_f32_32x32x16_bf16 v[64:79], v[204:207], v[126:129], v[64:79]
	v_exp_f32_e32 v84, v108
	v_exp_f32_e32 v85, v109
	v_exp_f32_e32 v86, v110
	v_exp_f32_e32 v87, v111
	v_add_f32_e32 v90, v84, v90
	v_add_f32_e32 v91, v85, v91
	v_add_f32_e32 v104, v86, v102
	v_add_f32_e32 v105, v87, v103
	v_cvt_pk_bf16_f32 v102, v84, v85
	v_cvt_pk_bf16_f32 v103, v86, v87
	s_waitcnt lgkmcnt(2)
	v_mfma_f32_32x32x16_bf16 v[48:63], v[208:211], v[126:129], v[48:63]
	v_exp_f32_e32 v92, v92
	v_exp_f32_e32 v93, v93
	v_exp_f32_e32 v94, v94
	v_exp_f32_e32 v95, v95
	v_add_f32_e32 v84, v92, v90
	v_add_f32_e32 v85, v93, v91
	v_add_f32_e32 v86, v94, v104
	v_add_f32_e32 v87, v95, v105
	v_cvt_pk_bf16_f32 v90, v92, v93
	v_cvt_pk_bf16_f32 v91, v94, v95
	s_waitcnt lgkmcnt(1)
	v_mfma_f32_32x32x16_bf16 v[64:79], v[212:215], v[130:133], v[64:79]
	s_waitcnt lgkmcnt(0)
	v_mfma_f32_32x32x16_bf16 v[48:63], v[146:149], v[130:133], v[48:63]
	v_add_f32_e32 v182, v84, v85
	v_add_f32_e32 v183, v86, v87
	v_add_f32_e32 v182, v182, v183
	v_add_f32_e32 v169, v169, v182
	s_waitcnt vmcnt(1)
	s_waitcnt lgkmcnt(0)
	s_barrier
	s_add_u32 s84, s84, 0x48000
	s_addc_u32 s85, s85, 0
	s_add_u32 s82, s82, 0x48000
	s_addc_u32 s83, s83, 0
	ds_read_b64_tr_b16 v[92:93], v180 offset:24576
	ds_read_b64_tr_b16 v[94:95], v180 offset:25088
	ds_read_b64_tr_b16 v[104:105], v180 offset:28672
	ds_read_b64_tr_b16 v[106:107], v180 offset:29184
	s_waitcnt lgkmcnt(2)
	v_mfma_f32_32x32x16_bf16 v[16:31], v[92:95], v[96:99], v[16:31]
	s_waitcnt lgkmcnt(0)
	v_mfma_f32_32x32x16_bf16 v[0:15], v[104:107], v[96:99], v[0:15]
	ds_read_b64_tr_b16 v[92:93], v180 offset:25600
	ds_read_b64_tr_b16 v[94:95], v180 offset:26112
	ds_read_b64_tr_b16 v[96:97], v180 offset:29696
	ds_read_b64_tr_b16 v[98:99], v180 offset:30208
	s_waitcnt lgkmcnt(2)
	v_mfma_f32_32x32x16_bf16 v[16:31], v[92:95], v[100:103], v[16:31]
	s_waitcnt lgkmcnt(0)
	v_mfma_f32_32x32x16_bf16 v[0:15], v[96:99], v[100:103], v[0:15]
	ds_read_b64_tr_b16 v[92:93], v180 offset:26624
	ds_read_b64_tr_b16 v[94:95], v180 offset:27136
	ds_read_b64_tr_b16 v[96:97], v180 offset:30720
	ds_read_b64_tr_b16 v[98:99], v180 offset:31232
	s_waitcnt lgkmcnt(2)
	v_mfma_f32_32x32x16_bf16 v[16:31], v[92:95], v[80:83], v[16:31]
	s_waitcnt lgkmcnt(0)
	v_mfma_f32_32x32x16_bf16 v[0:15], v[96:99], v[80:83], v[0:15]
	ds_read_b64_tr_b16 v[80:81], v180 offset:27648
	ds_read_b64_tr_b16 v[82:83], v180 offset:28160
	ds_read_b64_tr_b16 v[92:93], v180 offset:31744
	ds_read_b64_tr_b16 v[94:95], v180 offset:32256
	s_waitcnt lgkmcnt(2)
	v_mfma_f32_32x32x16_bf16 v[16:31], v[80:83], v[88:91], v[16:31]
	s_waitcnt lgkmcnt(0)
	v_mfma_f32_32x32x16_bf16 v[0:15], v[92:95], v[88:91], v[0:15]
	ds_read_b128 v[80:83], v179 offset:57344
	ds_read_b128 v[182:185], v179 offset:57856
	ds_read_b128 v[186:189], v179 offset:59392
	ds_read_b128 v[190:193], v179 offset:59904
	ds_read_b128 v[200:203], v179 offset:61440
	ds_read_b128 v[204:207], v179 offset:61952
	ds_read_b128 v[208:211], v179 offset:63488
	ds_read_b128 v[212:215], v179 offset:64000
	v_exp_f32_e32 v64, v64
	v_exp_f32_e32 v65, v65
	v_exp_f32_e32 v66, v66
	v_exp_f32_e32 v67, v67
	v_exp_f32_e32 v48, v48
	v_exp_f32_e32 v49, v49
	v_exp_f32_e32 v50, v50
	v_exp_f32_e32 v51, v51
	v_add_f32_e32 v84, v50, v66
	v_add_f32_e32 v85, v51, v67
	v_add_f32_e32 v86, v48, v64
	v_add_f32_e32 v87, v49, v65
	v_cvt_pk_bf16_f32 v64, v64, v65
	v_cvt_pk_bf16_f32 v65, v66, v67
	v_cvt_pk_bf16_f32 v48, v48, v49
	v_cvt_pk_bf16_f32 v49, v50, v51
	s_waitcnt lgkmcnt(7)
	v_mfma_f32_32x32x16_bf16 v[96:111], v[80:83], v[118:121], v[32:47]
	v_exp_f32_e32 v50, v68
	v_exp_f32_e32 v51, v69
	v_exp_f32_e32 v68, v70
	v_exp_f32_e32 v69, v71
	v_add_f32_e32 v70, v50, v86
	v_add_f32_e32 v71, v51, v87
	v_add_f32_e32 v181, v68, v84
	v_add_f32_e32 v228, v69, v85
	v_cvt_pk_bf16_f32 v66, v50, v51
	v_cvt_pk_bf16_f32 v67, v68, v69
	s_waitcnt lgkmcnt(6)
	v_mfma_f32_32x32x16_bf16 v[80:95], v[182:185], v[118:121], v[32:47]
	v_exp_f32_e32 v50, v52
	v_exp_f32_e32 v51, v53
	v_exp_f32_e32 v52, v54
	v_exp_f32_e32 v53, v55
	v_add_f32_e32 v54, v50, v70
	v_add_f32_e32 v55, v51, v71
	v_add_f32_e32 v68, v52, v181
	v_add_f32_e32 v69, v53, v228
	v_cvt_pk_bf16_f32 v50, v50, v51
	v_cvt_pk_bf16_f32 v51, v52, v53
	s_waitcnt lgkmcnt(5)
	v_mfma_f32_32x32x16_bf16 v[96:111], v[186:189], v[122:125], v[96:111]
	v_exp_f32_e32 v52, v72
	v_exp_f32_e32 v53, v73
	v_exp_f32_e32 v70, v74
	v_exp_f32_e32 v71, v75
	v_add_f32_e32 v54, v52, v54
	v_add_f32_e32 v55, v53, v55
	v_add_f32_e32 v72, v70, v68
	v_add_f32_e32 v73, v71, v69
	v_cvt_pk_bf16_f32 v68, v52, v53
	v_cvt_pk_bf16_f32 v69, v70, v71
	s_waitcnt lgkmcnt(4)
	v_mfma_f32_32x32x16_bf16 v[80:95], v[190:193], v[122:125], v[80:95]
	v_exp_f32_e32 v52, v56
	v_exp_f32_e32 v53, v57
	v_exp_f32_e32 v57, v58
	v_exp_f32_e32 v58, v59
	v_add_f32_e32 v54, v52, v54
	v_add_f32_e32 v55, v53, v55
	v_add_f32_e32 v59, v57, v72
	v_add_f32_e32 v70, v58, v73
	v_cvt_pk_bf16_f32 v56, v52, v53
	v_cvt_pk_bf16_f32 v57, v57, v58
	s_waitcnt lgkmcnt(3)
	v_mfma_f32_32x32x16_bf16 v[96:111], v[200:203], v[126:129], v[96:111]
	v_exp_f32_e32 v52, v76
	v_exp_f32_e32 v53, v77
	v_exp_f32_e32 v58, v78
	v_exp_f32_e32 v71, v79
	v_add_f32_e32 v54, v52, v54
	v_add_f32_e32 v55, v53, v55
	v_add_f32_e32 v59, v58, v59
	v_add_f32_e32 v72, v71, v70
	v_cvt_pk_bf16_f32 v70, v52, v53
	v_cvt_pk_bf16_f32 v71, v58, v71
	s_waitcnt lgkmcnt(2)
	v_mfma_f32_32x32x16_bf16 v[80:95], v[204:207], v[126:129], v[80:95]
	v_exp_f32_e32 v58, v60
	v_exp_f32_e32 v60, v61
	v_exp_f32_e32 v61, v62
	v_exp_f32_e32 v62, v63
	v_add_f32_e32 v52, v58, v54
	v_add_f32_e32 v53, v60, v55
	v_add_f32_e32 v54, v61, v59
	v_add_f32_e32 v55, v62, v72
	v_cvt_pk_bf16_f32 v58, v58, v60
	v_cvt_pk_bf16_f32 v59, v61, v62
	s_waitcnt lgkmcnt(1)
	v_mfma_f32_32x32x16_bf16 v[96:111], v[208:211], v[130:133], v[96:111]
	s_waitcnt lgkmcnt(0)
	v_mfma_f32_32x32x16_bf16 v[80:95], v[212:215], v[130:133], v[80:95]
	v_add_f32_e32 v182, v52, v53
	v_add_f32_e32 v183, v54, v55
	v_add_f32_e32 v182, v182, v183
	v_add_f32_e32 v169, v169, v182
	s_waitcnt vmcnt(0)
	s_waitcnt lgkmcnt(0)
	s_barrier
	s_add_u32 s84, s84, 0x48000
	s_addc_u32 s85, s85, 0
	s_add_u32 s82, s82, 0x48000
	s_addc_u32 s83, s83, 0
	ds_read_b64_tr_b16 v[60:61], v180 offset:32768
	ds_read_b64_tr_b16 v[62:63], v180 offset:33280
	ds_read_b64_tr_b16 v[72:73], v180 offset:36864
	ds_read_b64_tr_b16 v[74:75], v180 offset:37376
	s_waitcnt lgkmcnt(2)
	v_mfma_f32_32x32x16_bf16 v[16:31], v[60:63], v[64:67], v[16:31]
	s_waitcnt lgkmcnt(0)
	v_mfma_f32_32x32x16_bf16 v[0:15], v[72:75], v[64:67], v[0:15]
	ds_read_b64_tr_b16 v[60:61], v180 offset:33792
	ds_read_b64_tr_b16 v[62:63], v180 offset:34304
	ds_read_b64_tr_b16 v[64:65], v180 offset:37888
	ds_read_b64_tr_b16 v[66:67], v180 offset:38400
	s_waitcnt lgkmcnt(2)
	v_mfma_f32_32x32x16_bf16 v[16:31], v[60:63], v[68:71], v[16:31]
	s_waitcnt lgkmcnt(0)
	v_mfma_f32_32x32x16_bf16 v[0:15], v[64:67], v[68:71], v[0:15]
	ds_read_b64_tr_b16 v[60:61], v180 offset:34816
	ds_read_b64_tr_b16 v[62:63], v180 offset:35328
	ds_read_b64_tr_b16 v[64:65], v180 offset:38912
	ds_read_b64_tr_b16 v[66:67], v180 offset:39424
	s_waitcnt lgkmcnt(2)
	v_mfma_f32_32x32x16_bf16 v[16:31], v[60:63], v[48:51], v[16:31]
	s_waitcnt lgkmcnt(0)
	v_mfma_f32_32x32x16_bf16 v[0:15], v[64:67], v[48:51], v[0:15]
	ds_read_b64_tr_b16 v[48:49], v180 offset:35840
	ds_read_b64_tr_b16 v[50:51], v180 offset:36352
	ds_read_b64_tr_b16 v[60:61], v180 offset:39936
	ds_read_b64_tr_b16 v[62:63], v180 offset:40448
	s_waitcnt lgkmcnt(2)
	v_mfma_f32_32x32x16_bf16 v[16:31], v[48:51], v[56:59], v[16:31]
	s_waitcnt lgkmcnt(0)
	v_mfma_f32_32x32x16_bf16 v[0:15], v[60:63], v[56:59], v[0:15]
	v_exp_f32_e32 v64, v96
	v_exp_f32_e32 v65, v97
	v_exp_f32_e32 v66, v98
	v_exp_f32_e32 v67, v99
	v_cvt_pk_bf16_f32 v96, v64, v65
	v_cvt_pk_bf16_f32 v97, v66, v67
	v_exp_f32_e32 v68, v80
	v_exp_f32_e32 v69, v81
	v_exp_f32_e32 v70, v82
	v_exp_f32_e32 v71, v83
	v_cvt_pk_bf16_f32 v80, v68, v69
	v_cvt_pk_bf16_f32 v81, v70, v71
	v_add_f32_e32 v68, v68, v64
	v_add_f32_e32 v69, v69, v65
	v_add_f32_e32 v82, v70, v66
	v_add_f32_e32 v83, v71, v67
	v_exp_f32_e32 v98, v100
	v_exp_f32_e32 v99, v101
	v_exp_f32_e32 v100, v102
	v_exp_f32_e32 v101, v103
	v_add_f32_e32 v102, v98, v68
	v_add_f32_e32 v103, v99, v69
	v_add_f32_e32 v82, v100, v82
	v_add_f32_e32 v83, v101, v83
	v_cvt_pk_bf16_f32 v98, v98, v99
	v_cvt_pk_bf16_f32 v99, v100, v101
	v_exp_f32_e32 v84, v84
	v_exp_f32_e32 v85, v85
	v_exp_f32_e32 v86, v86
	v_exp_f32_e32 v87, v87
	v_add_f32_e32 v100, v84, v102
	v_add_f32_e32 v101, v85, v103
	v_add_f32_e32 v102, v86, v82
	v_add_f32_e32 v103, v87, v83
	v_cvt_pk_bf16_f32 v82, v84, v85
	v_cvt_pk_bf16_f32 v83, v86, v87
	v_exp_f32_e32 v84, v104
	v_exp_f32_e32 v85, v105
	v_exp_f32_e32 v86, v106
	v_exp_f32_e32 v87, v107
	v_add_f32_e32 v104, v84, v100
	v_add_f32_e32 v105, v85, v101
	v_add_f32_e32 v102, v86, v102
	v_add_f32_e32 v103, v87, v103
	v_cvt_pk_bf16_f32 v100, v84, v85
	v_cvt_pk_bf16_f32 v101, v86, v87
	v_exp_f32_e32 v84, v88
	v_exp_f32_e32 v85, v89
	v_exp_f32_e32 v86, v90
	v_exp_f32_e32 v87, v91
	v_add_f32_e32 v90, v84, v104
	v_add_f32_e32 v91, v85, v105
	v_add_f32_e32 v102, v86, v102
	v_add_f32_e32 v103, v87, v103
	v_cvt_pk_bf16_f32 v88, v84, v85
	v_cvt_pk_bf16_f32 v89, v86, v87
	v_exp_f32_e32 v84, v108
	v_exp_f32_e32 v85, v109
	v_exp_f32_e32 v86, v110
	v_exp_f32_e32 v87, v111
	v_add_f32_e32 v90, v84, v90
	v_add_f32_e32 v91, v85, v91
	v_add_f32_e32 v104, v86, v102
	v_add_f32_e32 v105, v87, v103
	v_cvt_pk_bf16_f32 v102, v84, v85
	v_cvt_pk_bf16_f32 v103, v86, v87
	v_exp_f32_e32 v92, v92
	v_exp_f32_e32 v93, v93
	v_exp_f32_e32 v94, v94
	v_exp_f32_e32 v95, v95
	v_add_f32_e32 v84, v92, v90
	v_add_f32_e32 v85, v93, v91
	v_add_f32_e32 v86, v94, v104
	v_add_f32_e32 v87, v95, v105
	v_cvt_pk_bf16_f32 v90, v92, v93
	v_cvt_pk_bf16_f32 v91, v94, v95
	v_add_f32_e32 v182, v84, v85
	v_add_f32_e32 v183, v86, v87
	v_add_f32_e32 v182, v182, v183
	v_add_f32_e32 v169, v169, v182
	s_waitcnt lgkmcnt(0)
	s_barrier
	ds_read_b64_tr_b16 v[92:93], v180 offset:40960
	ds_read_b64_tr_b16 v[94:95], v180 offset:41472
	ds_read_b64_tr_b16 v[104:105], v180 offset:45056
	ds_read_b64_tr_b16 v[106:107], v180 offset:45568
	s_waitcnt lgkmcnt(2)
	v_mfma_f32_32x32x16_bf16 v[16:31], v[92:95], v[96:99], v[16:31]
	s_waitcnt lgkmcnt(0)
	v_mfma_f32_32x32x16_bf16 v[0:15], v[104:107], v[96:99], v[0:15]
	ds_read_b64_tr_b16 v[92:93], v180 offset:41984
	ds_read_b64_tr_b16 v[94:95], v180 offset:42496
	ds_read_b64_tr_b16 v[96:97], v180 offset:46080
	ds_read_b64_tr_b16 v[98:99], v180 offset:46592
	s_waitcnt lgkmcnt(2)
	v_mfma_f32_32x32x16_bf16 v[16:31], v[92:95], v[100:103], v[16:31]
	s_waitcnt lgkmcnt(0)
	v_mfma_f32_32x32x16_bf16 v[0:15], v[96:99], v[100:103], v[0:15]
	ds_read_b64_tr_b16 v[92:93], v180 offset:43008
	ds_read_b64_tr_b16 v[94:95], v180 offset:43520
	ds_read_b64_tr_b16 v[96:97], v180 offset:47104
	ds_read_b64_tr_b16 v[98:99], v180 offset:47616
	s_waitcnt lgkmcnt(2)
	v_mfma_f32_32x32x16_bf16 v[16:31], v[92:95], v[80:83], v[16:31]
	s_waitcnt lgkmcnt(0)
	v_mfma_f32_32x32x16_bf16 v[0:15], v[96:99], v[80:83], v[0:15]
	ds_read_b64_tr_b16 v[80:81], v180 offset:44032
	ds_read_b64_tr_b16 v[82:83], v180 offset:44544
	ds_read_b64_tr_b16 v[92:93], v180 offset:48128
	ds_read_b64_tr_b16 v[94:95], v180 offset:48640
	s_waitcnt lgkmcnt(2)
	v_mfma_f32_32x32x16_bf16 v[16:31], v[80:83], v[88:91], v[16:31]
	s_waitcnt lgkmcnt(0)
	v_mfma_f32_32x32x16_bf16 v[0:15], v[92:95], v[88:91], v[0:15]
	s_branch .LBB0_62
